# MFMA order variant: zigzag row-fragment order in alternate groups so the A fragment pair repeats across group boundaries (plus hook, conversion, no K-loop setprio)
# speedup vs baseline: 1.0095x; 1.0095x over previous
.LBB0_120:
	s_and_b64 vcc, exec, s[6:7]
	s_cbranch_vccz .LBB0_122
	s_waitcnt lgkmcnt(0)
	ds_read_b128 v[4:7], v151
	ds_read_b128 v[8:11], v151 offset:1024
	ds_read_b128 v[12:15], v151 offset:2048
	ds_read_b128 v[16:19], v151 offset:3072
	ds_read_b128 v[20:23], v152
	ds_read_b128 v[24:27], v152 offset:1024
	ds_read_b128 v[28:31], v152 offset:2048
	ds_read_b128 v[32:35], v152 offset:3072
	s_or_b32 s9, s11, 0x100
	s_or_b32 s3, s11, 0x80180
	s_or_b32 s6, s10, 0x80100
	s_or_b32 s7, s11, 0x80100
	s_or_b32 s8, s11, 0x180
	s_or_b32 s12, s10, 0x100
	ds_read_b128 v[36:39], v153
	ds_read_b128 v[40:43], v153 offset:1024
	ds_read_b128 v[44:47], v153 offset:2048
	ds_read_b128 v[48:51], v153 offset:3072
	ds_read_b128 v[52:55], v153 offset:4096
	ds_read_b128 v[56:59], v153 offset:5120
	ds_read_b128 v[60:63], v153 offset:6144
	ds_read_b128 v[64:67], v153 offset:7168
	s_waitcnt vmcnt(24)
	s_waitcnt lgkmcnt(0)
	s_barrier
	s_setprio 1
	s_waitcnt lgkmcnt(1)
	v_mfma_f32_16x16x32_bf16 v[92:95], v[4:7], v[60:63], 0
	v_mfma_f32_16x16x32_bf16 v[68:71], v[4:7], v[36:39], 0
	v_mfma_f32_16x16x32_bf16 v[72:75], v[12:15], v[36:39], 0
	v_mfma_f32_16x16x32_bf16 v[76:79], v[4:7], v[44:47], 0
	v_mfma_f32_16x16x32_bf16 v[80:83], v[12:15], v[44:47], 0
	v_mfma_f32_16x16x32_bf16 v[84:87], v[4:7], v[52:55], 0
	v_mfma_f32_16x16x32_bf16 v[88:91], v[12:15], v[52:55], 0
	s_waitcnt lgkmcnt(0)
	v_mfma_f32_16x16x32_bf16 v[102:105], v[8:11], v[64:67], v[92:95]
	v_mfma_f32_16x16x32_bf16 v[92:95], v[12:15], v[60:63], 0
	v_mfma_f32_16x16x32_bf16 v[68:71], v[8:11], v[40:43], v[68:71]
	v_mfma_f32_16x16x32_bf16 v[76:79], v[8:11], v[48:51], v[76:79]
	v_mfma_f32_16x16x32_bf16 v[84:87], v[8:11], v[56:59], v[84:87]
	v_mfma_f32_16x16x32_bf16 v[106:109], v[16:19], v[64:67], v[92:95]
	v_mfma_f32_16x16x32_bf16 v[88:91], v[16:19], v[56:59], v[88:91]
	v_mfma_f32_16x16x32_bf16 v[80:83], v[16:19], v[48:51], v[80:83]
	v_mfma_f32_16x16x32_bf16 v[72:75], v[16:19], v[40:43], v[72:75]
	v_mfma_f32_16x16x32_bf16 v[92:95], v[20:23], v[36:39], 0
	v_mfma_f32_16x16x32_bf16 v[36:39], v[28:31], v[36:39], 0
	v_mfma_f32_16x16x32_bf16 v[118:121], v[24:27], v[40:43], v[92:95]
	v_mfma_f32_16x16x32_bf16 v[36:39], v[32:35], v[40:43], v[36:39]
	v_mfma_f32_16x16x32_bf16 v[40:43], v[20:23], v[44:47], 0
	v_mfma_f32_16x16x32_bf16 v[44:47], v[28:31], v[44:47], 0
	v_mfma_f32_16x16x32_bf16 v[40:43], v[24:27], v[48:51], v[40:43]
	v_mfma_f32_16x16x32_bf16 v[44:47], v[32:35], v[48:51], v[44:47]
	v_mfma_f32_16x16x32_bf16 v[48:51], v[20:23], v[52:55], 0
	v_mfma_f32_16x16x32_bf16 v[52:55], v[28:31], v[52:55], 0
	v_mfma_f32_16x16x32_bf16 v[48:51], v[24:27], v[56:59], v[48:51]
	v_mfma_f32_16x16x32_bf16 v[52:55], v[32:35], v[56:59], v[52:55]
	v_mfma_f32_16x16x32_bf16 v[56:59], v[20:23], v[60:63], 0
	v_mfma_f32_16x16x32_bf16 v[60:63], v[28:31], v[60:63], 0
	v_mfma_f32_16x16x32_bf16 v[56:59], v[24:27], v[64:67], v[56:59]
	v_mfma_f32_16x16x32_bf16 v[60:63], v[32:35], v[64:67], v[60:63]
	s_setprio 0
	s_barrier
	s_mov_b32 m0, s91
	s_mov_b32 s75, s31
	ds_read_b128 v[64:67], v153 offset:16384
	ds_read_b128 v[92:95], v153 offset:17408
	buffer_load_dwordx4 v146, s[72:75], s9 offen lds
	s_mov_b32 m0, s93
	ds_read_b128 v[96:99], v153 offset:18432
	ds_read_b128 v[110:113], v153 offset:19456
	buffer_load_dwordx4 v148, s[72:75], s9 offen lds
	s_mov_b32 m0, s95
	ds_read_b128 v[114:117], v153 offset:20480
	ds_read_b128 v[122:125], v153 offset:21504
	buffer_load_dwordx4 v146, s[72:75], s7 offen lds
	s_mov_b32 m0, s35
	ds_read_b128 v[126:129], v153 offset:22528
	ds_read_b128 v[130:133], v153 offset:23552
	buffer_load_dwordx4 v148, s[72:75], s7 offen lds
	s_waitcnt vmcnt(22)
	s_waitcnt lgkmcnt(0)
	s_barrier
	s_setprio 1
	s_waitcnt lgkmcnt(7)
	v_mfma_f32_16x16x32_bf16 v[138:141], v[4:7], v[64:67], 0
	s_waitcnt lgkmcnt(5)
	v_mfma_f32_16x16x32_bf16 v[158:161], v[4:7], v[96:99], 0
	s_waitcnt lgkmcnt(3)
	v_mfma_f32_16x16x32_bf16 v[166:169], v[4:7], v[114:117], 0
	s_waitcnt lgkmcnt(1)
	v_mfma_f32_16x16x32_bf16 v[4:7], v[4:7], v[126:129], 0
	s_waitcnt lgkmcnt(0)
	v_mfma_f32_16x16x32_bf16 v[138:141], v[8:11], v[92:95], v[138:141]
	v_mfma_f32_16x16x32_bf16 v[158:161], v[8:11], v[110:113], v[158:161]
	v_mfma_f32_16x16x32_bf16 v[166:169], v[8:11], v[122:125], v[166:169]
	v_mfma_f32_16x16x32_bf16 v[4:7], v[8:11], v[130:133], v[4:7]
	v_mfma_f32_16x16x32_bf16 v[8:11], v[12:15], v[126:129], 0
	v_mfma_f32_16x16x32_bf16 v[142:145], v[12:15], v[64:67], 0
	v_mfma_f32_16x16x32_bf16 v[162:165], v[12:15], v[96:99], 0
	v_mfma_f32_16x16x32_bf16 v[170:173], v[12:15], v[114:117], 0
	v_mfma_f32_16x16x32_bf16 v[8:11], v[16:19], v[130:133], v[8:11]
	v_mfma_f32_16x16x32_bf16 v[142:145], v[16:19], v[92:95], v[142:145]
	v_mfma_f32_16x16x32_bf16 v[162:165], v[16:19], v[110:113], v[162:165]
	v_mfma_f32_16x16x32_bf16 v[170:173], v[16:19], v[122:125], v[170:173]
	v_mfma_f32_16x16x32_bf16 v[12:15], v[20:23], v[64:67], 0
	v_mfma_f32_16x16x32_bf16 v[174:177], v[24:27], v[92:95], v[12:15]
	v_mfma_f32_16x16x32_bf16 v[12:15], v[28:31], v[64:67], 0
	v_mfma_f32_16x16x32_bf16 v[178:181], v[32:35], v[92:95], v[12:15]
	v_mfma_f32_16x16x32_bf16 v[12:15], v[20:23], v[96:99], 0
	v_mfma_f32_16x16x32_bf16 v[182:185], v[24:27], v[110:113], v[12:15]
	v_mfma_f32_16x16x32_bf16 v[12:15], v[28:31], v[96:99], 0
	v_mfma_f32_16x16x32_bf16 v[186:189], v[32:35], v[110:113], v[12:15]
	v_mfma_f32_16x16x32_bf16 v[12:15], v[20:23], v[114:117], 0
	v_mfma_f32_16x16x32_bf16 v[190:193], v[24:27], v[122:125], v[12:15]
	v_mfma_f32_16x16x32_bf16 v[12:15], v[28:31], v[114:117], 0
	v_mfma_f32_16x16x32_bf16 v[194:197], v[32:35], v[122:125], v[12:15]
	v_mfma_f32_16x16x32_bf16 v[12:15], v[20:23], v[126:129], 0
	v_mfma_f32_16x16x32_bf16 v[198:201], v[24:27], v[130:133], v[12:15]
	v_mfma_f32_16x16x32_bf16 v[12:15], v[28:31], v[126:129], 0
	v_mfma_f32_16x16x32_bf16 v[202:205], v[32:35], v[130:133], v[12:15]
	s_setprio 0
	s_barrier
	s_nop 4
	ds_read_b128 v[12:15], v154
	ds_read_b128 v[16:19], v154 offset:1024
	ds_read_b128 v[22:25], v154 offset:2048
	ds_read_b128 v[26:29], v154 offset:3072
	ds_read_b128 v[206:209], v155
	ds_read_b128 v[210:213], v155 offset:1024
	ds_read_b128 v[214:217], v155 offset:2048
	ds_read_b128 v[218:221], v155 offset:3072
	s_mov_b32 m0, s77
	ds_read_b128 v[30:33], v153 offset:32768
	ds_read_b128 v[64:67], v153 offset:33792
	buffer_load_dwordx4 v1, s[28:31], s12 offen lds
	s_mov_b32 m0, s84
	ds_read_b128 v[222:225], v153 offset:34816
	ds_read_b128 v[226:229], v153 offset:35840
	buffer_load_dwordx4 v147, s[28:31], s12 offen lds
	s_mov_b32 m0, s85
	ds_read_b128 v[230:233], v153 offset:36864
	ds_read_b128 v[236:239], v153 offset:37888
	buffer_load_dwordx4 v1, s[28:31], s6 offen lds
	s_mov_b32 m0, s48
	ds_read_b128 v[240:243], v153 offset:38912
	ds_read_b128 v[244:247], v153 offset:39936
	buffer_load_dwordx4 v147, s[28:31], s6 offen lds
	s_waitcnt vmcnt(24)
	s_waitcnt lgkmcnt(0)
	s_barrier
	s_setprio 1
	s_waitcnt lgkmcnt(0)
	v_mfma_f32_16x16x32_bf16 v[68:71], v[12:15], v[30:33], v[68:71]
	v_mfma_f32_16x16x32_bf16 v[130:133], v[16:19], v[64:67], v[68:71]
	v_mfma_f32_16x16x32_bf16 v[68:71], v[22:25], v[30:33], v[72:75]
	v_mfma_f32_16x16x32_bf16 v[126:129], v[26:29], v[64:67], v[68:71]
	v_mfma_f32_16x16x32_bf16 v[68:71], v[12:15], v[222:225], v[76:79]
	v_mfma_f32_16x16x32_bf16 v[114:117], v[16:19], v[226:229], v[68:71]
	v_mfma_f32_16x16x32_bf16 v[68:71], v[22:25], v[222:225], v[80:83]
	v_mfma_f32_16x16x32_bf16 v[110:113], v[26:29], v[226:229], v[68:71]
	v_mfma_f32_16x16x32_bf16 v[68:71], v[12:15], v[230:233], v[84:87]
	v_mfma_f32_16x16x32_bf16 v[98:101], v[16:19], v[236:239], v[68:71]
	v_mfma_f32_16x16x32_bf16 v[68:71], v[22:25], v[230:233], v[88:91]
	v_mfma_f32_16x16x32_bf16 v[94:97], v[26:29], v[236:239], v[68:71]
	v_mfma_f32_16x16x32_bf16 v[68:71], v[12:15], v[240:243], v[102:105]
	v_mfma_f32_16x16x32_bf16 v[82:85], v[16:19], v[244:247], v[68:71]
	v_mfma_f32_16x16x32_bf16 v[68:71], v[22:25], v[240:243], v[106:109]
	v_mfma_f32_16x16x32_bf16 v[78:81], v[26:29], v[244:247], v[68:71]
	v_mfma_f32_16x16x32_bf16 v[68:71], v[206:209], v[30:33], v[118:121]
	v_mfma_f32_16x16x32_bf16 v[122:125], v[210:213], v[64:67], v[68:71]
	v_mfma_f32_16x16x32_bf16 v[30:33], v[214:217], v[30:33], v[36:39]
	v_mfma_f32_16x16x32_bf16 v[118:121], v[218:221], v[64:67], v[30:33]
	v_mfma_f32_16x16x32_bf16 v[30:33], v[206:209], v[222:225], v[40:43]
	v_mfma_f32_16x16x32_bf16 v[106:109], v[210:213], v[226:229], v[30:33]
	v_mfma_f32_16x16x32_bf16 v[30:33], v[214:217], v[222:225], v[44:47]
	v_mfma_f32_16x16x32_bf16 v[102:105], v[218:221], v[226:229], v[30:33]
	v_mfma_f32_16x16x32_bf16 v[30:33], v[206:209], v[230:233], v[48:51]
	v_mfma_f32_16x16x32_bf16 v[90:93], v[210:213], v[236:239], v[30:33]
	v_mfma_f32_16x16x32_bf16 v[30:33], v[214:217], v[230:233], v[52:55]
	v_mfma_f32_16x16x32_bf16 v[86:89], v[218:221], v[236:239], v[30:33]
	v_mfma_f32_16x16x32_bf16 v[30:33], v[206:209], v[240:243], v[56:59]
	v_mfma_f32_16x16x32_bf16 v[74:77], v[210:213], v[244:247], v[30:33]
	v_mfma_f32_16x16x32_bf16 v[30:33], v[214:217], v[240:243], v[60:63]
	v_mfma_f32_16x16x32_bf16 v[70:73], v[218:221], v[244:247], v[30:33]
	s_setprio 0
	s_barrier
	s_mov_b32 m0, s78
	ds_read_b128 v[38:41], v153 offset:49152
	ds_read_b128 v[42:45], v153 offset:50176
	buffer_load_dwordx4 v146, s[72:75], s8 offen lds
	s_mov_b32 m0, s79
	ds_read_b128 v[222:225], v153 offset:51200
	ds_read_b128 v[226:229], v153 offset:52224
	buffer_load_dwordx4 v148, s[72:75], s8 offen lds
	s_mov_b32 m0, s86
	ds_read_b128 v[230:233], v153 offset:53248
	ds_read_b128 v[236:239], v153 offset:54272
	buffer_load_dwordx4 v146, s[72:75], s3 offen lds
	s_mov_b32 m0, s87
	ds_read_b128 v[240:243], v153 offset:55296
	ds_read_b128 v[244:247], v153 offset:56320
	buffer_load_dwordx4 v148, s[72:75], s3 offen lds
	s_waitcnt vmcnt(6)
	s_waitcnt lgkmcnt(0)
	s_barrier
	s_setprio 1
	s_waitcnt lgkmcnt(0)
	v_mfma_f32_16x16x32_bf16 v[30:33], v[12:15], v[38:41], v[138:141]
	v_mfma_f32_16x16x32_bf16 v[66:69], v[16:19], v[42:45], v[30:33]
	v_mfma_f32_16x16x32_bf16 v[4:7], v[12:15], v[240:243], v[4:7]
	v_mfma_f32_16x16x32_bf16 v[30:33], v[22:25], v[38:41], v[142:145]
	v_mfma_f32_16x16x32_bf16 v[62:65], v[26:29], v[42:45], v[30:33]
	v_mfma_f32_16x16x32_bf16 v[30:33], v[12:15], v[222:225], v[158:161]
	v_mfma_f32_16x16x32_bf16 v[50:53], v[16:19], v[226:229], v[30:33]
	v_mfma_f32_16x16x32_bf16 v[30:33], v[22:25], v[222:225], v[162:165]
	v_mfma_f32_16x16x32_bf16 v[46:49], v[26:29], v[226:229], v[30:33]
	v_mfma_f32_16x16x32_bf16 v[30:33], v[12:15], v[230:233], v[166:169]
	v_mfma_f32_16x16x32_bf16 v[34:37], v[16:19], v[236:239], v[30:33]
	v_mfma_f32_16x16x32_bf16 v[18:21], v[16:19], v[244:247], v[4:7]
	v_mfma_f32_16x16x32_bf16 v[4:7], v[22:25], v[240:243], v[8:11]
	v_mfma_f32_16x16x32_bf16 v[14:17], v[26:29], v[244:247], v[4:7]
	v_mfma_f32_16x16x32_bf16 v[30:33], v[22:25], v[230:233], v[170:173]
	v_mfma_f32_16x16x32_bf16 v[30:33], v[26:29], v[236:239], v[30:33]
	v_mfma_f32_16x16x32_bf16 v[4:7], v[206:209], v[38:41], v[174:177]
	v_mfma_f32_16x16x32_bf16 v[58:61], v[210:213], v[42:45], v[4:7]
	v_mfma_f32_16x16x32_bf16 v[4:7], v[214:217], v[38:41], v[178:181]
	v_mfma_f32_16x16x32_bf16 v[54:57], v[218:221], v[42:45], v[4:7]
	v_mfma_f32_16x16x32_bf16 v[4:7], v[206:209], v[222:225], v[182:185]
	v_mfma_f32_16x16x32_bf16 v[42:45], v[210:213], v[226:229], v[4:7]
	v_mfma_f32_16x16x32_bf16 v[4:7], v[214:217], v[222:225], v[186:189]
	v_mfma_f32_16x16x32_bf16 v[38:41], v[218:221], v[226:229], v[4:7]
	v_mfma_f32_16x16x32_bf16 v[4:7], v[206:209], v[230:233], v[190:193]
	v_mfma_f32_16x16x32_bf16 v[26:29], v[210:213], v[236:239], v[4:7]
	v_mfma_f32_16x16x32_bf16 v[4:7], v[214:217], v[230:233], v[194:197]
	v_mfma_f32_16x16x32_bf16 v[22:25], v[218:221], v[236:239], v[4:7]
	v_mfma_f32_16x16x32_bf16 v[4:7], v[206:209], v[240:243], v[198:201]
	v_mfma_f32_16x16x32_bf16 v[10:13], v[210:213], v[244:247], v[4:7]
	v_mfma_f32_16x16x32_bf16 v[4:7], v[214:217], v[240:243], v[202:205]
	v_mfma_f32_16x16x32_bf16 v[6:9], v[218:221], v[244:247], v[4:7]
	s_setprio 0
	s_barrier
	s_mov_b32 s9, 2
	s_branch .LBB0_123

.LBB0_124:
	ds_read_b128 v[138:141], v151
	ds_read_b128 v[142:145], v151 offset:1024
	ds_read_b128 v[158:161], v151 offset:2048
	ds_read_b128 v[162:165], v151 offset:3072
	ds_read_b128 v[166:169], v152
	ds_read_b128 v[170:173], v152 offset:1024
	ds_read_b128 v[174:177], v152 offset:2048
	ds_read_b128 v[178:181], v152 offset:3072
	s_add_i32 s47, s9, s10
	s_add_i32 s75, s47, 0x100
	s_add_i32 s13, s9, s11
	s_cmp_eq_u32 s9, s12
	s_cselect_b32 s13, s7, s13
	s_cselect_b32 s80, s6, s75
	s_add_i32 s75, s47, 0x80
	s_mov_b32 m0, s58
	ds_read_b128 v[182:185], v153
	ds_read_b128 v[186:189], v153 offset:1024
	buffer_load_dwordx4 v1, s[28:31], s75 offen lds
	s_mov_b32 m0, s59
	ds_read_b128 v[190:193], v153 offset:2048
	ds_read_b128 v[194:197], v153 offset:3072
	buffer_load_dwordx4 v147, s[28:31], s75 offen lds
	s_add_i32 s47, s47, 0x80080
	s_mov_b32 m0, s70
	ds_read_b128 v[198:201], v153 offset:4096
	ds_read_b128 v[202:205], v153 offset:5120
	buffer_load_dwordx4 v1, s[28:31], s47 offen lds
	s_mov_b32 m0, s71
	ds_read_b128 v[206:209], v153 offset:6144
	ds_read_b128 v[210:213], v153 offset:7168
	buffer_load_dwordx4 v147, s[28:31], s47 offen lds
	s_waitcnt vmcnt(8)
	s_waitcnt lgkmcnt(0)
	s_barrier
	s_waitcnt lgkmcnt(0)
	v_mfma_f32_16x16x32_bf16 v[130:133], v[138:141], v[182:185], v[130:133]
	v_mfma_f32_16x16x32_bf16 v[130:133], v[142:145], v[186:189], v[130:133]
	v_mfma_f32_16x16x32_bf16 v[114:117], v[142:145], v[194:197], v[114:117]
	v_mfma_f32_16x16x32_bf16 v[114:117], v[138:141], v[190:193], v[114:117]
	v_mfma_f32_16x16x32_bf16 v[98:101], v[138:141], v[198:201], v[98:101]
	v_mfma_f32_16x16x32_bf16 v[98:101], v[142:145], v[202:205], v[98:101]
	v_mfma_f32_16x16x32_bf16 v[82:85], v[142:145], v[210:213], v[82:85]
	v_mfma_f32_16x16x32_bf16 v[82:85], v[138:141], v[206:209], v[82:85]
	v_mfma_f32_16x16x32_bf16 v[78:81], v[162:165], v[210:213], v[78:81]
	v_mfma_f32_16x16x32_bf16 v[78:81], v[158:161], v[206:209], v[78:81]
	v_mfma_f32_16x16x32_bf16 v[94:97], v[158:161], v[198:201], v[94:97]
	v_mfma_f32_16x16x32_bf16 v[94:97], v[162:165], v[202:205], v[94:97]
	v_mfma_f32_16x16x32_bf16 v[110:113], v[162:165], v[194:197], v[110:113]
	v_mfma_f32_16x16x32_bf16 v[110:113], v[158:161], v[190:193], v[110:113]
	v_mfma_f32_16x16x32_bf16 v[126:129], v[158:161], v[182:185], v[126:129]
	v_mfma_f32_16x16x32_bf16 v[126:129], v[162:165], v[186:189], v[126:129]
	v_mfma_f32_16x16x32_bf16 v[122:125], v[166:169], v[182:185], v[122:125]
	v_mfma_f32_16x16x32_bf16 v[122:125], v[170:173], v[186:189], v[122:125]
	v_mfma_f32_16x16x32_bf16 v[106:109], v[170:173], v[194:197], v[106:109]
	v_mfma_f32_16x16x32_bf16 v[106:109], v[166:169], v[190:193], v[106:109]
	v_mfma_f32_16x16x32_bf16 v[90:93], v[166:169], v[198:201], v[90:93]
	v_mfma_f32_16x16x32_bf16 v[90:93], v[170:173], v[202:205], v[90:93]
	v_mfma_f32_16x16x32_bf16 v[74:77], v[170:173], v[210:213], v[74:77]
	v_mfma_f32_16x16x32_bf16 v[74:77], v[166:169], v[206:209], v[74:77]
	v_mfma_f32_16x16x32_bf16 v[70:73], v[178:181], v[210:213], v[70:73]
	v_mfma_f32_16x16x32_bf16 v[70:73], v[174:177], v[206:209], v[70:73]
	v_mfma_f32_16x16x32_bf16 v[86:89], v[174:177], v[198:201], v[86:89]
	v_mfma_f32_16x16x32_bf16 v[86:89], v[178:181], v[202:205], v[86:89]
	v_mfma_f32_16x16x32_bf16 v[102:105], v[178:181], v[194:197], v[102:105]
	v_mfma_f32_16x16x32_bf16 v[102:105], v[174:177], v[190:193], v[102:105]
	v_mfma_f32_16x16x32_bf16 v[118:121], v[174:177], v[182:185], v[118:121]
	v_mfma_f32_16x16x32_bf16 v[118:121], v[178:181], v[186:189], v[118:121]
	s_barrier
	s_mov_b32 m0, s91
	s_mov_b32 s75, s31
	ds_read_b128 v[182:185], v153 offset:16384
	ds_read_b128 v[186:189], v153 offset:17408
	buffer_load_dwordx4 v146, s[72:75], s13 offen lds
	s_mov_b32 m0, s93
	ds_read_b128 v[190:193], v153 offset:18432
	ds_read_b128 v[194:197], v153 offset:19456
	buffer_load_dwordx4 v148, s[72:75], s13 offen lds
	s_add_i32 s47, s13, 0x80000
	s_mov_b32 m0, s95
	ds_read_b128 v[198:201], v153 offset:20480
	ds_read_b128 v[202:205], v153 offset:21504
	buffer_load_dwordx4 v146, s[72:75], s47 offen lds
	s_mov_b32 m0, s35
	ds_read_b128 v[206:209], v153 offset:22528
	ds_read_b128 v[210:213], v153 offset:23552
	buffer_load_dwordx4 v148, s[72:75], s47 offen lds
	s_waitcnt vmcnt(6)
	s_waitcnt lgkmcnt(0)
	s_barrier
	s_waitcnt lgkmcnt(0)
	v_mfma_f32_16x16x32_bf16 v[66:69], v[138:141], v[182:185], v[66:69]
	v_mfma_f32_16x16x32_bf16 v[66:69], v[142:145], v[186:189], v[66:69]
	v_mfma_f32_16x16x32_bf16 v[50:53], v[142:145], v[194:197], v[50:53]
	v_mfma_f32_16x16x32_bf16 v[50:53], v[138:141], v[190:193], v[50:53]
	v_mfma_f32_16x16x32_bf16 v[34:37], v[138:141], v[198:201], v[34:37]
	v_mfma_f32_16x16x32_bf16 v[34:37], v[142:145], v[202:205], v[34:37]
	v_mfma_f32_16x16x32_bf16 v[18:21], v[142:145], v[210:213], v[18:21]
	v_mfma_f32_16x16x32_bf16 v[18:21], v[138:141], v[206:209], v[18:21]
	v_mfma_f32_16x16x32_bf16 v[14:17], v[162:165], v[210:213], v[14:17]
	v_mfma_f32_16x16x32_bf16 v[14:17], v[158:161], v[206:209], v[14:17]
	v_mfma_f32_16x16x32_bf16 v[30:33], v[158:161], v[198:201], v[30:33]
	v_mfma_f32_16x16x32_bf16 v[30:33], v[162:165], v[202:205], v[30:33]
	v_mfma_f32_16x16x32_bf16 v[46:49], v[162:165], v[194:197], v[46:49]
	v_mfma_f32_16x16x32_bf16 v[46:49], v[158:161], v[190:193], v[46:49]
	v_mfma_f32_16x16x32_bf16 v[62:65], v[158:161], v[182:185], v[62:65]
	v_mfma_f32_16x16x32_bf16 v[62:65], v[162:165], v[186:189], v[62:65]
	v_mfma_f32_16x16x32_bf16 v[58:61], v[166:169], v[182:185], v[58:61]
	v_mfma_f32_16x16x32_bf16 v[58:61], v[170:173], v[186:189], v[58:61]
	v_mfma_f32_16x16x32_bf16 v[42:45], v[170:173], v[194:197], v[42:45]
	v_mfma_f32_16x16x32_bf16 v[42:45], v[166:169], v[190:193], v[42:45]
	v_mfma_f32_16x16x32_bf16 v[26:29], v[166:169], v[198:201], v[26:29]
	v_mfma_f32_16x16x32_bf16 v[26:29], v[170:173], v[202:205], v[26:29]
	v_mfma_f32_16x16x32_bf16 v[10:13], v[170:173], v[210:213], v[10:13]
	v_mfma_f32_16x16x32_bf16 v[10:13], v[166:169], v[206:209], v[10:13]
	v_mfma_f32_16x16x32_bf16 v[4:7], v[174:177], v[206:209], v[6:9]
	v_mfma_f32_16x16x32_bf16 v[4:7], v[178:181], v[210:213], v[4:7]
	v_mfma_f32_16x16x32_bf16 v[22:25], v[174:177], v[198:201], v[22:25]
	v_mfma_f32_16x16x32_bf16 v[22:25], v[178:181], v[202:205], v[22:25]
	v_mfma_f32_16x16x32_bf16 v[38:41], v[178:181], v[194:197], v[38:41]
	v_mfma_f32_16x16x32_bf16 v[38:41], v[174:177], v[190:193], v[38:41]
	v_mfma_f32_16x16x32_bf16 v[54:57], v[174:177], v[182:185], v[54:57]
	v_mfma_f32_16x16x32_bf16 v[54:57], v[178:181], v[186:189], v[54:57]
	s_barrier
	ds_read_b128 v[138:141], v154
	ds_read_b128 v[142:145], v154 offset:1024
	ds_read_b128 v[158:161], v154 offset:2048
	ds_read_b128 v[162:165], v154 offset:3072
	ds_read_b128 v[166:169], v155
	ds_read_b128 v[170:173], v155 offset:1024
	ds_read_b128 v[174:177], v155 offset:2048
	ds_read_b128 v[178:181], v155 offset:3072
	s_mov_b32 m0, s77
	ds_read_b128 v[182:185], v153 offset:32768
	ds_read_b128 v[186:189], v153 offset:33792
	buffer_load_dwordx4 v1, s[28:31], s80 offen lds
	s_mov_b32 m0, s84
	ds_read_b128 v[190:193], v153 offset:34816
	ds_read_b128 v[194:197], v153 offset:35840
	buffer_load_dwordx4 v147, s[28:31], s80 offen lds
	s_add_i32 s80, s80, 0x80000
	s_mov_b32 m0, s85
	ds_read_b128 v[198:201], v153 offset:36864
	ds_read_b128 v[202:205], v153 offset:37888
	buffer_load_dwordx4 v1, s[28:31], s80 offen lds
	s_mov_b32 m0, s48
	ds_read_b128 v[206:209], v153 offset:38912
	ds_read_b128 v[210:213], v153 offset:39936
	buffer_load_dwordx4 v147, s[28:31], s80 offen lds
	s_waitcnt vmcnt(8)
	s_waitcnt lgkmcnt(0)
	s_barrier
	s_waitcnt lgkmcnt(0)
	v_mfma_f32_16x16x32_bf16 v[130:133], v[138:141], v[182:185], v[130:133]
	v_mfma_f32_16x16x32_bf16 v[130:133], v[142:145], v[186:189], v[130:133]
	v_mfma_f32_16x16x32_bf16 v[114:117], v[142:145], v[194:197], v[114:117]
	v_mfma_f32_16x16x32_bf16 v[114:117], v[138:141], v[190:193], v[114:117]
	v_mfma_f32_16x16x32_bf16 v[98:101], v[138:141], v[198:201], v[98:101]
	v_mfma_f32_16x16x32_bf16 v[98:101], v[142:145], v[202:205], v[98:101]
	v_mfma_f32_16x16x32_bf16 v[82:85], v[142:145], v[210:213], v[82:85]
	v_mfma_f32_16x16x32_bf16 v[82:85], v[138:141], v[206:209], v[82:85]
	v_mfma_f32_16x16x32_bf16 v[78:81], v[162:165], v[210:213], v[78:81]
	v_mfma_f32_16x16x32_bf16 v[78:81], v[158:161], v[206:209], v[78:81]
	v_mfma_f32_16x16x32_bf16 v[94:97], v[158:161], v[198:201], v[94:97]
	v_mfma_f32_16x16x32_bf16 v[94:97], v[162:165], v[202:205], v[94:97]
	v_mfma_f32_16x16x32_bf16 v[110:113], v[162:165], v[194:197], v[110:113]
	v_mfma_f32_16x16x32_bf16 v[110:113], v[158:161], v[190:193], v[110:113]
	v_mfma_f32_16x16x32_bf16 v[126:129], v[158:161], v[182:185], v[126:129]
	v_mfma_f32_16x16x32_bf16 v[126:129], v[162:165], v[186:189], v[126:129]
	v_mfma_f32_16x16x32_bf16 v[122:125], v[166:169], v[182:185], v[122:125]
	v_mfma_f32_16x16x32_bf16 v[122:125], v[170:173], v[186:189], v[122:125]
	v_mfma_f32_16x16x32_bf16 v[106:109], v[170:173], v[194:197], v[106:109]
	v_mfma_f32_16x16x32_bf16 v[106:109], v[166:169], v[190:193], v[106:109]
	v_mfma_f32_16x16x32_bf16 v[90:93], v[166:169], v[198:201], v[90:93]
	v_mfma_f32_16x16x32_bf16 v[90:93], v[170:173], v[202:205], v[90:93]
	v_mfma_f32_16x16x32_bf16 v[74:77], v[170:173], v[210:213], v[74:77]
	v_mfma_f32_16x16x32_bf16 v[74:77], v[166:169], v[206:209], v[74:77]
	v_mfma_f32_16x16x32_bf16 v[70:73], v[178:181], v[210:213], v[70:73]
	v_mfma_f32_16x16x32_bf16 v[70:73], v[174:177], v[206:209], v[70:73]
	v_mfma_f32_16x16x32_bf16 v[86:89], v[174:177], v[198:201], v[86:89]
	v_mfma_f32_16x16x32_bf16 v[86:89], v[178:181], v[202:205], v[86:89]
	v_mfma_f32_16x16x32_bf16 v[102:105], v[178:181], v[194:197], v[102:105]
	v_mfma_f32_16x16x32_bf16 v[102:105], v[174:177], v[190:193], v[102:105]
	v_mfma_f32_16x16x32_bf16 v[118:121], v[174:177], v[182:185], v[118:121]
	v_mfma_f32_16x16x32_bf16 v[118:121], v[178:181], v[186:189], v[118:121]
	s_barrier
	s_mov_b32 m0, s78
	s_add_i32 s47, s13, 0x80
	ds_read_b128 v[182:185], v153 offset:49152
	ds_read_b128 v[186:189], v153 offset:50176
	buffer_load_dwordx4 v146, s[72:75], s47 offen lds
	s_mov_b32 m0, s79
	ds_read_b128 v[190:193], v153 offset:51200
	ds_read_b128 v[194:197], v153 offset:52224
	buffer_load_dwordx4 v148, s[72:75], s47 offen lds
	s_add_i32 s13, s13, 0x80080
	s_mov_b32 m0, s86
	ds_read_b128 v[198:201], v153 offset:53248
	ds_read_b128 v[202:205], v153 offset:54272
	buffer_load_dwordx4 v146, s[72:75], s13 offen lds
	s_mov_b32 m0, s87
	ds_read_b128 v[206:209], v153 offset:55296
	ds_read_b128 v[210:213], v153 offset:56320
	buffer_load_dwordx4 v148, s[72:75], s13 offen lds
	s_waitcnt vmcnt(6)
	s_waitcnt lgkmcnt(0)
	s_barrier
	s_waitcnt lgkmcnt(0)
	v_mfma_f32_16x16x32_bf16 v[66:69], v[138:141], v[182:185], v[66:69]
	v_mfma_f32_16x16x32_bf16 v[66:69], v[142:145], v[186:189], v[66:69]
	v_mfma_f32_16x16x32_bf16 v[50:53], v[142:145], v[194:197], v[50:53]
	v_mfma_f32_16x16x32_bf16 v[50:53], v[138:141], v[190:193], v[50:53]
	v_mfma_f32_16x16x32_bf16 v[34:37], v[138:141], v[198:201], v[34:37]
	v_mfma_f32_16x16x32_bf16 v[34:37], v[142:145], v[202:205], v[34:37]
	v_mfma_f32_16x16x32_bf16 v[18:21], v[142:145], v[210:213], v[18:21]
	v_mfma_f32_16x16x32_bf16 v[18:21], v[138:141], v[206:209], v[18:21]
	v_mfma_f32_16x16x32_bf16 v[14:17], v[162:165], v[210:213], v[14:17]
	v_mfma_f32_16x16x32_bf16 v[14:17], v[158:161], v[206:209], v[14:17]
	v_mfma_f32_16x16x32_bf16 v[30:33], v[158:161], v[198:201], v[30:33]
	v_mfma_f32_16x16x32_bf16 v[30:33], v[162:165], v[202:205], v[30:33]
	v_mfma_f32_16x16x32_bf16 v[46:49], v[162:165], v[194:197], v[46:49]
	v_mfma_f32_16x16x32_bf16 v[46:49], v[158:161], v[190:193], v[46:49]
	v_mfma_f32_16x16x32_bf16 v[62:65], v[158:161], v[182:185], v[62:65]
	v_mfma_f32_16x16x32_bf16 v[62:65], v[162:165], v[186:189], v[62:65]
	v_mfma_f32_16x16x32_bf16 v[58:61], v[166:169], v[182:185], v[58:61]
	v_mfma_f32_16x16x32_bf16 v[58:61], v[170:173], v[186:189], v[58:61]
	v_mfma_f32_16x16x32_bf16 v[42:45], v[170:173], v[194:197], v[42:45]
	v_mfma_f32_16x16x32_bf16 v[42:45], v[166:169], v[190:193], v[42:45]
	v_mfma_f32_16x16x32_bf16 v[26:29], v[166:169], v[198:201], v[26:29]
	v_mfma_f32_16x16x32_bf16 v[26:29], v[170:173], v[202:205], v[26:29]
	v_mfma_f32_16x16x32_bf16 v[8:11], v[166:169], v[206:209], v[10:13]
	v_mfma_f32_16x16x32_bf16 v[10:13], v[170:173], v[210:213], v[8:11]
	v_mfma_f32_16x16x32_bf16 v[4:7], v[174:177], v[206:209], v[4:7]
	v_mfma_f32_16x16x32_bf16 v[6:9], v[178:181], v[210:213], v[4:7]
	v_mfma_f32_16x16x32_bf16 v[22:25], v[174:177], v[198:201], v[22:25]
	v_mfma_f32_16x16x32_bf16 v[22:25], v[178:181], v[202:205], v[22:25]
	v_mfma_f32_16x16x32_bf16 v[38:41], v[178:181], v[194:197], v[38:41]
	v_mfma_f32_16x16x32_bf16 v[38:41], v[174:177], v[190:193], v[38:41]
	v_mfma_f32_16x16x32_bf16 v[54:57], v[174:177], v[182:185], v[54:57]
	v_mfma_f32_16x16x32_bf16 v[54:57], v[178:181], v[186:189], v[54:57]
	s_barrier
	s_add_i32 s8, s8, 2
	s_addk_i32 s10, 0x100
	s_addk_i32 s11, 0x100
	s_addk_i32 s12, 0xff00
	s_cmp_gt_u32 s8, 29
	s_cbranch_scc0 .LBB0_124
	v_readlane_b32 s6, v254, 26
	v_readlane_b32 s7, v254, 27
	s_and_b64 vcc, exec, s[6:7]
	s_cbranch_vccz .LBB0_127
	s_barrier

.LBB0_528:
	v_add_u32_e32 v3, 0x10000, v171
	ds_read_b128 v[134:137], v3
	ds_read_b128 v[138:141], v3 offset:1024
	ds_read_b128 v[142:145], v3 offset:2048
	ds_read_b128 v[146:149], v3 offset:3072
	v_add_u32_e32 v3, 0x14000, v171
	ds_read_b128 v[150:153], v3
	ds_read_b128 v[154:157], v3 offset:1024
	ds_read_b128 v[174:177], v3 offset:2048
	ds_read_b128 v[178:181], v3 offset:3072
	s_add_i32 s71, s63, s94
	s_add_i32 s97, s71, 0x100
	s_add_i32 s96, s63, s95
	s_cmp_eq_u32 s63, s93
	s_cselect_b32 s96, s90, s96
	s_cselect_b32 s97, s89, s97
	s_add_i32 vcc_lo, s71, 0x80
	s_mov_b32 m0, s79
	ds_read_b128 v[182:185], v172
	ds_read_b128 v[186:189], v172 offset:1024
	buffer_load_dwordx4 v1, s[48:51], vcc_lo offen lds
	s_mov_b32 m0, s80
	ds_read_b128 v[190:193], v172 offset:2048
	ds_read_b128 v[194:197], v172 offset:3072
	buffer_load_dwordx4 v167, s[48:51], vcc_lo offen lds
	s_add_i32 s71, s71, 0xc0080
	s_mov_b32 m0, s81
	ds_read_b128 v[198:201], v172 offset:4096
	ds_read_b128 v[202:205], v172 offset:5120
	buffer_load_dwordx4 v1, s[48:51], s71 offen lds
	s_mov_b32 m0, s82
	ds_read_b128 v[206:209], v172 offset:6144
	ds_read_b128 v[210:213], v172 offset:7168
	buffer_load_dwordx4 v167, s[48:51], s71 offen lds
	s_waitcnt vmcnt(8)
	s_waitcnt lgkmcnt(0)
	s_barrier
	s_waitcnt lgkmcnt(0)
	v_mfma_f32_16x16x32_bf16 v[130:133], v[134:137], v[182:185], v[130:133]
	v_mfma_f32_16x16x32_bf16 v[130:133], v[138:141], v[186:189], v[130:133]
	v_mfma_f32_16x16x32_bf16 v[114:117], v[138:141], v[194:197], v[114:117]
	v_mfma_f32_16x16x32_bf16 v[114:117], v[134:137], v[190:193], v[114:117]
	v_mfma_f32_16x16x32_bf16 v[98:101], v[134:137], v[198:201], v[98:101]
	v_mfma_f32_16x16x32_bf16 v[98:101], v[138:141], v[202:205], v[98:101]
	v_mfma_f32_16x16x32_bf16 v[82:85], v[138:141], v[210:213], v[82:85]
	v_mfma_f32_16x16x32_bf16 v[82:85], v[134:137], v[206:209], v[82:85]
	v_mfma_f32_16x16x32_bf16 v[78:81], v[146:149], v[210:213], v[78:81]
	v_mfma_f32_16x16x32_bf16 v[78:81], v[142:145], v[206:209], v[78:81]
	v_mfma_f32_16x16x32_bf16 v[94:97], v[142:145], v[198:201], v[94:97]
	v_mfma_f32_16x16x32_bf16 v[94:97], v[146:149], v[202:205], v[94:97]
	v_mfma_f32_16x16x32_bf16 v[110:113], v[146:149], v[194:197], v[110:113]
	v_mfma_f32_16x16x32_bf16 v[110:113], v[142:145], v[190:193], v[110:113]
	v_mfma_f32_16x16x32_bf16 v[126:129], v[142:145], v[182:185], v[126:129]
	v_mfma_f32_16x16x32_bf16 v[126:129], v[146:149], v[186:189], v[126:129]
	v_mfma_f32_16x16x32_bf16 v[122:125], v[150:153], v[182:185], v[122:125]
	v_mfma_f32_16x16x32_bf16 v[122:125], v[154:157], v[186:189], v[122:125]
	v_mfma_f32_16x16x32_bf16 v[106:109], v[154:157], v[194:197], v[106:109]
	v_mfma_f32_16x16x32_bf16 v[106:109], v[150:153], v[190:193], v[106:109]
	v_mfma_f32_16x16x32_bf16 v[90:93], v[150:153], v[198:201], v[90:93]
	v_mfma_f32_16x16x32_bf16 v[90:93], v[154:157], v[202:205], v[90:93]
	v_mfma_f32_16x16x32_bf16 v[74:77], v[154:157], v[210:213], v[74:77]
	v_mfma_f32_16x16x32_bf16 v[74:77], v[150:153], v[206:209], v[74:77]
	v_mfma_f32_16x16x32_bf16 v[70:73], v[178:181], v[210:213], v[70:73]
	v_mfma_f32_16x16x32_bf16 v[70:73], v[174:177], v[206:209], v[70:73]
	v_mfma_f32_16x16x32_bf16 v[86:89], v[174:177], v[198:201], v[86:89]
	v_mfma_f32_16x16x32_bf16 v[86:89], v[178:181], v[202:205], v[86:89]
	v_mfma_f32_16x16x32_bf16 v[102:105], v[178:181], v[194:197], v[102:105]
	v_mfma_f32_16x16x32_bf16 v[102:105], v[174:177], v[190:193], v[102:105]
	v_mfma_f32_16x16x32_bf16 v[118:121], v[174:177], v[182:185], v[118:121]
	v_mfma_f32_16x16x32_bf16 v[118:121], v[178:181], v[186:189], v[118:121]
	s_barrier
	s_mov_b32 m0, s35
	s_mov_b32 s71, s51
	ds_read_b128 v[182:185], v172 offset:16384
	ds_read_b128 v[186:189], v172 offset:17408
	buffer_load_dwordx4 v166, s[68:71], s96 offen lds
	s_mov_b32 m0, s45
	ds_read_b128 v[190:193], v172 offset:18432
	ds_read_b128 v[194:197], v172 offset:19456
	buffer_load_dwordx4 v168, s[68:71], s96 offen lds
	s_add_i32 vcc_lo, s96, 0xc0000
	s_mov_b32 m0, s64
	ds_read_b128 v[198:201], v172 offset:20480
	ds_read_b128 v[202:205], v172 offset:21504
	buffer_load_dwordx4 v166, s[68:71], vcc_lo offen lds
	s_mov_b32 m0, s65
	ds_read_b128 v[206:209], v172 offset:22528
	ds_read_b128 v[210:213], v172 offset:23552
	buffer_load_dwordx4 v168, s[68:71], vcc_lo offen lds
	s_waitcnt vmcnt(6)
	s_waitcnt lgkmcnt(0)
	s_barrier
	s_waitcnt lgkmcnt(0)
	v_mfma_f32_16x16x32_bf16 v[66:69], v[134:137], v[182:185], v[66:69]
	v_mfma_f32_16x16x32_bf16 v[66:69], v[138:141], v[186:189], v[66:69]
	v_mfma_f32_16x16x32_bf16 v[50:53], v[138:141], v[194:197], v[50:53]
	v_mfma_f32_16x16x32_bf16 v[50:53], v[134:137], v[190:193], v[50:53]
	v_mfma_f32_16x16x32_bf16 v[34:37], v[134:137], v[198:201], v[34:37]
	v_mfma_f32_16x16x32_bf16 v[34:37], v[138:141], v[202:205], v[34:37]
	v_mfma_f32_16x16x32_bf16 v[18:21], v[138:141], v[210:213], v[18:21]
	v_mfma_f32_16x16x32_bf16 v[18:21], v[134:137], v[206:209], v[18:21]
	v_mfma_f32_16x16x32_bf16 v[14:17], v[146:149], v[210:213], v[14:17]
	v_mfma_f32_16x16x32_bf16 v[14:17], v[142:145], v[206:209], v[14:17]
	v_mfma_f32_16x16x32_bf16 v[30:33], v[142:145], v[198:201], v[30:33]
	v_mfma_f32_16x16x32_bf16 v[30:33], v[146:149], v[202:205], v[30:33]
	v_mfma_f32_16x16x32_bf16 v[46:49], v[146:149], v[194:197], v[46:49]
	v_mfma_f32_16x16x32_bf16 v[46:49], v[142:145], v[190:193], v[46:49]
	v_mfma_f32_16x16x32_bf16 v[62:65], v[142:145], v[182:185], v[62:65]
	v_mfma_f32_16x16x32_bf16 v[62:65], v[146:149], v[186:189], v[62:65]
	v_mfma_f32_16x16x32_bf16 v[58:61], v[150:153], v[182:185], v[58:61]
	v_mfma_f32_16x16x32_bf16 v[58:61], v[154:157], v[186:189], v[58:61]
	v_mfma_f32_16x16x32_bf16 v[42:45], v[154:157], v[194:197], v[42:45]
	v_mfma_f32_16x16x32_bf16 v[42:45], v[150:153], v[190:193], v[42:45]
	v_mfma_f32_16x16x32_bf16 v[26:29], v[150:153], v[198:201], v[26:29]
	v_mfma_f32_16x16x32_bf16 v[26:29], v[154:157], v[202:205], v[26:29]
	v_mfma_f32_16x16x32_bf16 v[10:13], v[154:157], v[210:213], v[10:13]
	v_mfma_f32_16x16x32_bf16 v[10:13], v[150:153], v[206:209], v[10:13]
	v_mfma_f32_16x16x32_bf16 v[4:7], v[174:177], v[206:209], v[6:9]
	v_mfma_f32_16x16x32_bf16 v[4:7], v[178:181], v[210:213], v[4:7]
	v_mfma_f32_16x16x32_bf16 v[22:25], v[174:177], v[198:201], v[22:25]
	v_mfma_f32_16x16x32_bf16 v[22:25], v[178:181], v[202:205], v[22:25]
	v_mfma_f32_16x16x32_bf16 v[38:41], v[178:181], v[194:197], v[38:41]
	v_mfma_f32_16x16x32_bf16 v[38:41], v[174:177], v[190:193], v[38:41]
	v_mfma_f32_16x16x32_bf16 v[54:57], v[174:177], v[182:185], v[54:57]
	v_mfma_f32_16x16x32_bf16 v[54:57], v[178:181], v[186:189], v[54:57]
	s_barrier
	v_add_u32_e32 v3, 0x18000, v171
	ds_read_b128 v[134:137], v3
	ds_read_b128 v[138:141], v3 offset:1024
	ds_read_b128 v[142:145], v3 offset:2048
	ds_read_b128 v[146:149], v3 offset:3072
	v_add_u32_e32 v3, 0x1c000, v171
	ds_read_b128 v[150:153], v3
	ds_read_b128 v[154:157], v3 offset:1024
	ds_read_b128 v[174:177], v3 offset:2048
	ds_read_b128 v[178:181], v3 offset:3072
	s_mov_b32 m0, s29
	ds_read_b128 v[182:185], v172 offset:32768
	ds_read_b128 v[186:189], v172 offset:33792
	buffer_load_dwordx4 v1, s[48:51], s97 offen lds
	s_mov_b32 m0, s66
	ds_read_b128 v[190:193], v172 offset:34816
	ds_read_b128 v[194:197], v172 offset:35840
	buffer_load_dwordx4 v167, s[48:51], s97 offen lds
	s_add_i32 s97, s97, 0xc0000
	s_mov_b32 m0, s67
	ds_read_b128 v[198:201], v172 offset:36864
	ds_read_b128 v[202:205], v172 offset:37888
	buffer_load_dwordx4 v1, s[48:51], s97 offen lds
	s_mov_b32 m0, s72
	ds_read_b128 v[206:209], v172 offset:38912
	ds_read_b128 v[210:213], v172 offset:39936
	buffer_load_dwordx4 v167, s[48:51], s97 offen lds
	s_waitcnt vmcnt(8)
	s_waitcnt lgkmcnt(0)
	s_barrier
	s_waitcnt lgkmcnt(0)
	v_mfma_f32_16x16x32_bf16 v[130:133], v[134:137], v[182:185], v[130:133]
	v_mfma_f32_16x16x32_bf16 v[130:133], v[138:141], v[186:189], v[130:133]
	v_mfma_f32_16x16x32_bf16 v[114:117], v[138:141], v[194:197], v[114:117]
	v_mfma_f32_16x16x32_bf16 v[114:117], v[134:137], v[190:193], v[114:117]
	v_mfma_f32_16x16x32_bf16 v[98:101], v[134:137], v[198:201], v[98:101]
	v_mfma_f32_16x16x32_bf16 v[98:101], v[138:141], v[202:205], v[98:101]
	v_mfma_f32_16x16x32_bf16 v[82:85], v[138:141], v[210:213], v[82:85]
	v_mfma_f32_16x16x32_bf16 v[82:85], v[134:137], v[206:209], v[82:85]
	v_mfma_f32_16x16x32_bf16 v[78:81], v[146:149], v[210:213], v[78:81]
	v_mfma_f32_16x16x32_bf16 v[78:81], v[142:145], v[206:209], v[78:81]
	v_mfma_f32_16x16x32_bf16 v[94:97], v[142:145], v[198:201], v[94:97]
	v_mfma_f32_16x16x32_bf16 v[94:97], v[146:149], v[202:205], v[94:97]
	v_mfma_f32_16x16x32_bf16 v[110:113], v[146:149], v[194:197], v[110:113]
	v_mfma_f32_16x16x32_bf16 v[110:113], v[142:145], v[190:193], v[110:113]
	v_mfma_f32_16x16x32_bf16 v[126:129], v[142:145], v[182:185], v[126:129]
	v_mfma_f32_16x16x32_bf16 v[126:129], v[146:149], v[186:189], v[126:129]
	v_mfma_f32_16x16x32_bf16 v[122:125], v[150:153], v[182:185], v[122:125]
	v_mfma_f32_16x16x32_bf16 v[122:125], v[154:157], v[186:189], v[122:125]
	v_mfma_f32_16x16x32_bf16 v[106:109], v[154:157], v[194:197], v[106:109]
	v_mfma_f32_16x16x32_bf16 v[106:109], v[150:153], v[190:193], v[106:109]
	v_mfma_f32_16x16x32_bf16 v[90:93], v[150:153], v[198:201], v[90:93]
	v_mfma_f32_16x16x32_bf16 v[90:93], v[154:157], v[202:205], v[90:93]
	v_mfma_f32_16x16x32_bf16 v[74:77], v[154:157], v[210:213], v[74:77]
	v_mfma_f32_16x16x32_bf16 v[74:77], v[150:153], v[206:209], v[74:77]
	v_mfma_f32_16x16x32_bf16 v[70:73], v[178:181], v[210:213], v[70:73]
	v_mfma_f32_16x16x32_bf16 v[70:73], v[174:177], v[206:209], v[70:73]
	v_mfma_f32_16x16x32_bf16 v[86:89], v[174:177], v[198:201], v[86:89]
	v_mfma_f32_16x16x32_bf16 v[86:89], v[178:181], v[202:205], v[86:89]
	v_mfma_f32_16x16x32_bf16 v[102:105], v[178:181], v[194:197], v[102:105]
	v_mfma_f32_16x16x32_bf16 v[102:105], v[174:177], v[190:193], v[102:105]
	v_mfma_f32_16x16x32_bf16 v[118:121], v[174:177], v[182:185], v[118:121]
	v_mfma_f32_16x16x32_bf16 v[118:121], v[178:181], v[186:189], v[118:121]
	s_barrier
	s_mov_b32 m0, s74
	s_add_i32 s97, s96, 0x80
	ds_read_b128 v[182:185], v172 offset:49152
	ds_read_b128 v[186:189], v172 offset:50176
	buffer_load_dwordx4 v166, s[68:71], s97 offen lds
	s_mov_b32 m0, s75
	ds_read_b128 v[190:193], v172 offset:51200
	ds_read_b128 v[194:197], v172 offset:52224
	buffer_load_dwordx4 v168, s[68:71], s97 offen lds
	s_add_i32 s96, s96, 0xc0080
	s_mov_b32 m0, s77
	ds_read_b128 v[198:201], v172 offset:53248
	ds_read_b128 v[202:205], v172 offset:54272
	buffer_load_dwordx4 v166, s[68:71], s96 offen lds
	s_mov_b32 m0, s78
	ds_read_b128 v[206:209], v172 offset:55296
	ds_read_b128 v[210:213], v172 offset:56320
	buffer_load_dwordx4 v168, s[68:71], s96 offen lds
	s_waitcnt vmcnt(6)
	s_waitcnt lgkmcnt(0)
	s_barrier
	s_waitcnt lgkmcnt(0)
	v_mfma_f32_16x16x32_bf16 v[66:69], v[134:137], v[182:185], v[66:69]
	v_mfma_f32_16x16x32_bf16 v[66:69], v[138:141], v[186:189], v[66:69]
	v_mfma_f32_16x16x32_bf16 v[50:53], v[138:141], v[194:197], v[50:53]
	v_mfma_f32_16x16x32_bf16 v[50:53], v[134:137], v[190:193], v[50:53]
	v_mfma_f32_16x16x32_bf16 v[34:37], v[134:137], v[198:201], v[34:37]
	v_mfma_f32_16x16x32_bf16 v[34:37], v[138:141], v[202:205], v[34:37]
	v_mfma_f32_16x16x32_bf16 v[18:21], v[138:141], v[210:213], v[18:21]
	v_mfma_f32_16x16x32_bf16 v[18:21], v[134:137], v[206:209], v[18:21]
	v_mfma_f32_16x16x32_bf16 v[14:17], v[146:149], v[210:213], v[14:17]
	v_mfma_f32_16x16x32_bf16 v[14:17], v[142:145], v[206:209], v[14:17]
	v_mfma_f32_16x16x32_bf16 v[30:33], v[142:145], v[198:201], v[30:33]
	v_mfma_f32_16x16x32_bf16 v[30:33], v[146:149], v[202:205], v[30:33]
	v_mfma_f32_16x16x32_bf16 v[46:49], v[146:149], v[194:197], v[46:49]
	v_mfma_f32_16x16x32_bf16 v[46:49], v[142:145], v[190:193], v[46:49]
	v_mfma_f32_16x16x32_bf16 v[62:65], v[142:145], v[182:185], v[62:65]
	v_mfma_f32_16x16x32_bf16 v[62:65], v[146:149], v[186:189], v[62:65]
	v_mfma_f32_16x16x32_bf16 v[58:61], v[150:153], v[182:185], v[58:61]
	v_mfma_f32_16x16x32_bf16 v[58:61], v[154:157], v[186:189], v[58:61]
	v_mfma_f32_16x16x32_bf16 v[42:45], v[154:157], v[194:197], v[42:45]
	v_mfma_f32_16x16x32_bf16 v[42:45], v[150:153], v[190:193], v[42:45]
	v_mfma_f32_16x16x32_bf16 v[26:29], v[150:153], v[198:201], v[26:29]
	v_mfma_f32_16x16x32_bf16 v[26:29], v[154:157], v[202:205], v[26:29]
	v_mfma_f32_16x16x32_bf16 v[8:11], v[150:153], v[206:209], v[10:13]
	v_mfma_f32_16x16x32_bf16 v[10:13], v[154:157], v[210:213], v[8:11]
	v_mfma_f32_16x16x32_bf16 v[4:7], v[174:177], v[206:209], v[4:7]
	v_mfma_f32_16x16x32_bf16 v[6:9], v[178:181], v[210:213], v[4:7]
	v_mfma_f32_16x16x32_bf16 v[22:25], v[174:177], v[198:201], v[22:25]
	v_mfma_f32_16x16x32_bf16 v[22:25], v[178:181], v[202:205], v[22:25]
	v_mfma_f32_16x16x32_bf16 v[38:41], v[178:181], v[194:197], v[38:41]
	v_mfma_f32_16x16x32_bf16 v[38:41], v[174:177], v[190:193], v[38:41]
	v_mfma_f32_16x16x32_bf16 v[54:57], v[174:177], v[182:185], v[54:57]
	v_mfma_f32_16x16x32_bf16 v[54:57], v[178:181], v[186:189], v[54:57]
	s_barrier
	s_add_i32 s92, s92, 2
	s_addk_i32 s95, 0x100
	s_addk_i32 s94, 0x100
	s_addk_i32 s93, 0xff00
	s_cmp_ge_u32 s92, s62
	s_cbranch_scc0 .LBB0_528
	s_branch .LBB0_523

.LBB0_605:
	v_add_u32_e32 v141, 0x10000, v139
	ds_read_b128 v[142:145], v141
	ds_read_b128 v[146:149], v141 offset:1024
	ds_read_b128 v[154:157], v141 offset:2048
	ds_read_b128 v[158:161], v141 offset:3072
	v_add_u32_e32 v141, 0x14000, v139
	ds_read_b128 v[162:165], v141
	ds_read_b128 v[166:169], v141 offset:1024
	ds_read_b128 v[170:173], v141 offset:2048
	ds_read_b128 v[174:177], v141 offset:3072
	s_add_i32 s47, s64, s82
	s_add_i32 s84, s47, 0x100
	s_add_i32 s83, s11, s82
	s_cmpk_eq_i32 s82, 0xf00
	s_cselect_b32 s83, s80, s83
	s_cselect_b32 s84, s79, s84
	s_add_i32 s85, s47, 0x80
	s_mov_b32 m0, s71
	ds_read_b128 v[178:181], v140
	ds_read_b128 v[182:185], v140 offset:1024
	buffer_load_dwordx4 v135, s[12:15], s85 offen lds
	s_mov_b32 m0, s72
	ds_read_b128 v[186:189], v140 offset:2048
	ds_read_b128 v[190:193], v140 offset:3072
	buffer_load_dwordx4 v137, s[12:15], s85 offen lds
	s_add_i32 s47, s47, 0x80080
	s_mov_b32 m0, s73
	ds_read_b128 v[194:197], v140 offset:4096
	ds_read_b128 v[198:201], v140 offset:5120
	buffer_load_dwordx4 v135, s[12:15], s47 offen lds
	s_mov_b32 m0, s74
	ds_read_b128 v[202:205], v140 offset:6144
	ds_read_b128 v[206:209], v140 offset:7168
	buffer_load_dwordx4 v137, s[12:15], s47 offen lds
	s_waitcnt vmcnt(8)
	s_waitcnt lgkmcnt(0)
	s_barrier
	s_waitcnt lgkmcnt(0)
	v_mfma_f32_16x16x32_bf16 v[126:129], v[142:145], v[178:181], v[126:129]
	v_mfma_f32_16x16x32_bf16 v[126:129], v[146:149], v[182:185], v[126:129]
	v_mfma_f32_16x16x32_bf16 v[110:113], v[146:149], v[190:193], v[110:113]
	v_mfma_f32_16x16x32_bf16 v[110:113], v[142:145], v[186:189], v[110:113]
	v_mfma_f32_16x16x32_bf16 v[94:97], v[142:145], v[194:197], v[94:97]
	v_mfma_f32_16x16x32_bf16 v[94:97], v[146:149], v[198:201], v[94:97]
	v_mfma_f32_16x16x32_bf16 v[78:81], v[146:149], v[206:209], v[78:81]
	v_mfma_f32_16x16x32_bf16 v[78:81], v[142:145], v[202:205], v[78:81]
	v_mfma_f32_16x16x32_bf16 v[74:77], v[158:161], v[206:209], v[74:77]
	v_mfma_f32_16x16x32_bf16 v[74:77], v[154:157], v[202:205], v[74:77]
	v_mfma_f32_16x16x32_bf16 v[90:93], v[154:157], v[194:197], v[90:93]
	v_mfma_f32_16x16x32_bf16 v[90:93], v[158:161], v[198:201], v[90:93]
	v_mfma_f32_16x16x32_bf16 v[106:109], v[158:161], v[190:193], v[106:109]
	v_mfma_f32_16x16x32_bf16 v[106:109], v[154:157], v[186:189], v[106:109]
	v_mfma_f32_16x16x32_bf16 v[122:125], v[154:157], v[178:181], v[122:125]
	v_mfma_f32_16x16x32_bf16 v[122:125], v[158:161], v[182:185], v[122:125]
	v_mfma_f32_16x16x32_bf16 v[118:121], v[162:165], v[178:181], v[118:121]
	v_mfma_f32_16x16x32_bf16 v[118:121], v[166:169], v[182:185], v[118:121]
	v_mfma_f32_16x16x32_bf16 v[102:105], v[166:169], v[190:193], v[102:105]
	v_mfma_f32_16x16x32_bf16 v[102:105], v[162:165], v[186:189], v[102:105]
	v_mfma_f32_16x16x32_bf16 v[86:89], v[162:165], v[194:197], v[86:89]
	v_mfma_f32_16x16x32_bf16 v[86:89], v[166:169], v[198:201], v[86:89]
	v_mfma_f32_16x16x32_bf16 v[70:73], v[166:169], v[206:209], v[70:73]
	v_mfma_f32_16x16x32_bf16 v[70:73], v[162:165], v[202:205], v[70:73]
	v_mfma_f32_16x16x32_bf16 v[66:69], v[174:177], v[206:209], v[66:69]
	v_mfma_f32_16x16x32_bf16 v[66:69], v[170:173], v[202:205], v[66:69]
	v_mfma_f32_16x16x32_bf16 v[82:85], v[170:173], v[194:197], v[82:85]
	v_mfma_f32_16x16x32_bf16 v[82:85], v[174:177], v[198:201], v[82:85]
	v_mfma_f32_16x16x32_bf16 v[98:101], v[174:177], v[190:193], v[98:101]
	v_mfma_f32_16x16x32_bf16 v[98:101], v[170:173], v[186:189], v[98:101]
	v_mfma_f32_16x16x32_bf16 v[114:117], v[170:173], v[178:181], v[114:117]
	v_mfma_f32_16x16x32_bf16 v[114:117], v[174:177], v[182:185], v[114:117]
	s_barrier
	s_mov_b32 m0, s58
	s_mov_b32 s47, s15
	ds_read_b128 v[178:181], v140 offset:16384
	ds_read_b128 v[182:185], v140 offset:17408
	buffer_load_dwordx4 v136, s[44:47], s83 offen lds
	s_mov_b32 m0, s60
	ds_read_b128 v[186:189], v140 offset:18432
	ds_read_b128 v[190:193], v140 offset:19456
	buffer_load_dwordx4 v138, s[44:47], s83 offen lds
	s_add_i32 s85, s83, 0x80000
	s_mov_b32 m0, s61
	ds_read_b128 v[194:197], v140 offset:20480
	ds_read_b128 v[198:201], v140 offset:21504
	buffer_load_dwordx4 v136, s[44:47], s85 offen lds
	s_mov_b32 m0, s62
	ds_read_b128 v[202:205], v140 offset:22528
	ds_read_b128 v[206:209], v140 offset:23552
	buffer_load_dwordx4 v138, s[44:47], s85 offen lds
	s_waitcnt vmcnt(6)
	s_waitcnt lgkmcnt(0)
	s_barrier
	s_waitcnt lgkmcnt(0)
	v_mfma_f32_16x16x32_bf16 v[62:65], v[142:145], v[178:181], v[62:65]
	v_mfma_f32_16x16x32_bf16 v[62:65], v[146:149], v[182:185], v[62:65]
	v_mfma_f32_16x16x32_bf16 v[46:49], v[146:149], v[190:193], v[46:49]
	v_mfma_f32_16x16x32_bf16 v[46:49], v[142:145], v[186:189], v[46:49]
	v_mfma_f32_16x16x32_bf16 v[30:33], v[142:145], v[194:197], v[30:33]
	v_mfma_f32_16x16x32_bf16 v[30:33], v[146:149], v[198:201], v[30:33]
	v_mfma_f32_16x16x32_bf16 v[14:17], v[146:149], v[206:209], v[14:17]
	v_mfma_f32_16x16x32_bf16 v[14:17], v[142:145], v[202:205], v[14:17]
	v_mfma_f32_16x16x32_bf16 v[10:13], v[158:161], v[206:209], v[10:13]
	v_mfma_f32_16x16x32_bf16 v[10:13], v[154:157], v[202:205], v[10:13]
	v_mfma_f32_16x16x32_bf16 v[26:29], v[154:157], v[194:197], v[26:29]
	v_mfma_f32_16x16x32_bf16 v[26:29], v[158:161], v[198:201], v[26:29]
	v_mfma_f32_16x16x32_bf16 v[42:45], v[158:161], v[190:193], v[42:45]
	v_mfma_f32_16x16x32_bf16 v[42:45], v[154:157], v[186:189], v[42:45]
	v_mfma_f32_16x16x32_bf16 v[58:61], v[154:157], v[178:181], v[58:61]
	v_mfma_f32_16x16x32_bf16 v[58:61], v[158:161], v[182:185], v[58:61]
	v_mfma_f32_16x16x32_bf16 v[54:57], v[162:165], v[178:181], v[54:57]
	v_mfma_f32_16x16x32_bf16 v[54:57], v[166:169], v[182:185], v[54:57]
	v_mfma_f32_16x16x32_bf16 v[38:41], v[166:169], v[190:193], v[38:41]
	v_mfma_f32_16x16x32_bf16 v[38:41], v[162:165], v[186:189], v[38:41]
	v_mfma_f32_16x16x32_bf16 v[22:25], v[162:165], v[194:197], v[22:25]
	v_mfma_f32_16x16x32_bf16 v[22:25], v[166:169], v[198:201], v[22:25]
	v_mfma_f32_16x16x32_bf16 v[6:9], v[166:169], v[206:209], v[6:9]
	v_mfma_f32_16x16x32_bf16 v[6:9], v[162:165], v[202:205], v[6:9]
	v_mfma_f32_16x16x32_bf16 v[2:5], v[174:177], v[206:209], v[2:5]
	v_mfma_f32_16x16x32_bf16 v[2:5], v[170:173], v[202:205], v[2:5]
	v_mfma_f32_16x16x32_bf16 v[18:21], v[170:173], v[194:197], v[18:21]
	v_mfma_f32_16x16x32_bf16 v[18:21], v[174:177], v[198:201], v[18:21]
	v_mfma_f32_16x16x32_bf16 v[34:37], v[174:177], v[190:193], v[34:37]
	v_mfma_f32_16x16x32_bf16 v[34:37], v[170:173], v[186:189], v[34:37]
	v_mfma_f32_16x16x32_bf16 v[50:53], v[170:173], v[178:181], v[50:53]
	v_mfma_f32_16x16x32_bf16 v[50:53], v[174:177], v[182:185], v[50:53]
	s_barrier
	v_add_u32_e32 v141, 0x18000, v139
	ds_read_b128 v[142:145], v141
	ds_read_b128 v[146:149], v141 offset:1024
	ds_read_b128 v[154:157], v141 offset:2048
	ds_read_b128 v[158:161], v141 offset:3072
	v_add_u32_e32 v141, 0x1c000, v139
	ds_read_b128 v[162:165], v141
	ds_read_b128 v[166:169], v141 offset:1024
	ds_read_b128 v[170:173], v141 offset:2048
	ds_read_b128 v[174:177], v141 offset:3072
	s_mov_b32 m0, s51
	ds_read_b128 v[178:181], v140 offset:32768
	ds_read_b128 v[182:185], v140 offset:33792
	buffer_load_dwordx4 v135, s[12:15], s84 offen lds
	s_mov_b32 m0, s63
	ds_read_b128 v[186:189], v140 offset:34816
	ds_read_b128 v[190:193], v140 offset:35840
	buffer_load_dwordx4 v137, s[12:15], s84 offen lds
	s_add_i32 s84, s84, 0x80000
	s_mov_b32 m0, s65
	ds_read_b128 v[194:197], v140 offset:36864
	ds_read_b128 v[198:201], v140 offset:37888
	buffer_load_dwordx4 v135, s[12:15], s84 offen lds
	s_mov_b32 m0, s66
	ds_read_b128 v[202:205], v140 offset:38912
	ds_read_b128 v[206:209], v140 offset:39936
	buffer_load_dwordx4 v137, s[12:15], s84 offen lds
	s_waitcnt vmcnt(8)
	s_waitcnt lgkmcnt(0)
	s_barrier
	s_waitcnt lgkmcnt(0)
	v_mfma_f32_16x16x32_bf16 v[126:129], v[142:145], v[178:181], v[126:129]
	v_mfma_f32_16x16x32_bf16 v[126:129], v[146:149], v[182:185], v[126:129]
	v_mfma_f32_16x16x32_bf16 v[110:113], v[146:149], v[190:193], v[110:113]
	v_mfma_f32_16x16x32_bf16 v[110:113], v[142:145], v[186:189], v[110:113]
	v_mfma_f32_16x16x32_bf16 v[94:97], v[142:145], v[194:197], v[94:97]
	v_mfma_f32_16x16x32_bf16 v[94:97], v[146:149], v[198:201], v[94:97]
	v_mfma_f32_16x16x32_bf16 v[78:81], v[146:149], v[206:209], v[78:81]
	v_mfma_f32_16x16x32_bf16 v[78:81], v[142:145], v[202:205], v[78:81]
	v_mfma_f32_16x16x32_bf16 v[74:77], v[158:161], v[206:209], v[74:77]
	v_mfma_f32_16x16x32_bf16 v[74:77], v[154:157], v[202:205], v[74:77]
	v_mfma_f32_16x16x32_bf16 v[90:93], v[154:157], v[194:197], v[90:93]
	v_mfma_f32_16x16x32_bf16 v[90:93], v[158:161], v[198:201], v[90:93]
	v_mfma_f32_16x16x32_bf16 v[106:109], v[158:161], v[190:193], v[106:109]
	v_mfma_f32_16x16x32_bf16 v[106:109], v[154:157], v[186:189], v[106:109]
	v_mfma_f32_16x16x32_bf16 v[122:125], v[154:157], v[178:181], v[122:125]
	v_mfma_f32_16x16x32_bf16 v[122:125], v[158:161], v[182:185], v[122:125]
	v_mfma_f32_16x16x32_bf16 v[118:121], v[162:165], v[178:181], v[118:121]
	v_mfma_f32_16x16x32_bf16 v[118:121], v[166:169], v[182:185], v[118:121]
	v_mfma_f32_16x16x32_bf16 v[102:105], v[166:169], v[190:193], v[102:105]
	v_mfma_f32_16x16x32_bf16 v[102:105], v[162:165], v[186:189], v[102:105]
	v_mfma_f32_16x16x32_bf16 v[86:89], v[162:165], v[194:197], v[86:89]
	v_mfma_f32_16x16x32_bf16 v[86:89], v[166:169], v[198:201], v[86:89]
	v_mfma_f32_16x16x32_bf16 v[70:73], v[166:169], v[206:209], v[70:73]
	v_mfma_f32_16x16x32_bf16 v[70:73], v[162:165], v[202:205], v[70:73]
	v_mfma_f32_16x16x32_bf16 v[66:69], v[174:177], v[206:209], v[66:69]
	v_mfma_f32_16x16x32_bf16 v[66:69], v[170:173], v[202:205], v[66:69]
	v_mfma_f32_16x16x32_bf16 v[82:85], v[170:173], v[194:197], v[82:85]
	v_mfma_f32_16x16x32_bf16 v[82:85], v[174:177], v[198:201], v[82:85]
	v_mfma_f32_16x16x32_bf16 v[98:101], v[174:177], v[190:193], v[98:101]
	v_mfma_f32_16x16x32_bf16 v[98:101], v[170:173], v[186:189], v[98:101]
	v_mfma_f32_16x16x32_bf16 v[114:117], v[170:173], v[178:181], v[114:117]
	v_mfma_f32_16x16x32_bf16 v[114:117], v[174:177], v[182:185], v[114:117]
	s_barrier
	s_mov_b32 m0, s67
	s_or_b32 s84, s83, 0x80
	ds_read_b128 v[178:181], v140 offset:49152
	ds_read_b128 v[182:185], v140 offset:50176
	buffer_load_dwordx4 v136, s[44:47], s84 offen lds
	s_mov_b32 m0, s68
	ds_read_b128 v[186:189], v140 offset:51200
	ds_read_b128 v[190:193], v140 offset:52224
	buffer_load_dwordx4 v138, s[44:47], s84 offen lds
	s_add_i32 s83, s83, 0x80080
	s_mov_b32 m0, s69
	ds_read_b128 v[194:197], v140 offset:53248
	ds_read_b128 v[198:201], v140 offset:54272
	buffer_load_dwordx4 v136, s[44:47], s83 offen lds
	s_mov_b32 m0, s70
	ds_read_b128 v[202:205], v140 offset:55296
	ds_read_b128 v[206:209], v140 offset:56320
	buffer_load_dwordx4 v138, s[44:47], s83 offen lds
	s_waitcnt vmcnt(6)
	s_waitcnt lgkmcnt(0)
	s_barrier
	s_waitcnt lgkmcnt(0)
	v_mfma_f32_16x16x32_bf16 v[62:65], v[142:145], v[178:181], v[62:65]
	v_mfma_f32_16x16x32_bf16 v[62:65], v[146:149], v[182:185], v[62:65]
	v_mfma_f32_16x16x32_bf16 v[46:49], v[146:149], v[190:193], v[46:49]
	v_mfma_f32_16x16x32_bf16 v[46:49], v[142:145], v[186:189], v[46:49]
	v_mfma_f32_16x16x32_bf16 v[30:33], v[142:145], v[194:197], v[30:33]
	v_mfma_f32_16x16x32_bf16 v[30:33], v[146:149], v[198:201], v[30:33]
	v_mfma_f32_16x16x32_bf16 v[14:17], v[146:149], v[206:209], v[14:17]
	v_mfma_f32_16x16x32_bf16 v[14:17], v[142:145], v[202:205], v[14:17]
	v_mfma_f32_16x16x32_bf16 v[10:13], v[158:161], v[206:209], v[10:13]
	v_mfma_f32_16x16x32_bf16 v[10:13], v[154:157], v[202:205], v[10:13]
	v_mfma_f32_16x16x32_bf16 v[26:29], v[154:157], v[194:197], v[26:29]
	v_mfma_f32_16x16x32_bf16 v[26:29], v[158:161], v[198:201], v[26:29]
	v_mfma_f32_16x16x32_bf16 v[42:45], v[158:161], v[190:193], v[42:45]
	v_mfma_f32_16x16x32_bf16 v[42:45], v[154:157], v[186:189], v[42:45]
	v_mfma_f32_16x16x32_bf16 v[58:61], v[154:157], v[178:181], v[58:61]
	v_mfma_f32_16x16x32_bf16 v[58:61], v[158:161], v[182:185], v[58:61]
	v_mfma_f32_16x16x32_bf16 v[54:57], v[162:165], v[178:181], v[54:57]
	v_mfma_f32_16x16x32_bf16 v[54:57], v[166:169], v[182:185], v[54:57]
	v_mfma_f32_16x16x32_bf16 v[38:41], v[166:169], v[190:193], v[38:41]
	v_mfma_f32_16x16x32_bf16 v[38:41], v[162:165], v[186:189], v[38:41]
	v_mfma_f32_16x16x32_bf16 v[22:25], v[162:165], v[194:197], v[22:25]
	v_mfma_f32_16x16x32_bf16 v[22:25], v[166:169], v[198:201], v[22:25]
	v_mfma_f32_16x16x32_bf16 v[6:9], v[166:169], v[206:209], v[6:9]
	v_mfma_f32_16x16x32_bf16 v[6:9], v[162:165], v[202:205], v[6:9]
	v_mfma_f32_16x16x32_bf16 v[2:5], v[174:177], v[206:209], v[2:5]
	v_mfma_f32_16x16x32_bf16 v[2:5], v[170:173], v[202:205], v[2:5]
	v_mfma_f32_16x16x32_bf16 v[18:21], v[170:173], v[194:197], v[18:21]
	v_mfma_f32_16x16x32_bf16 v[18:21], v[174:177], v[198:201], v[18:21]
	v_mfma_f32_16x16x32_bf16 v[34:37], v[174:177], v[190:193], v[34:37]
	v_mfma_f32_16x16x32_bf16 v[34:37], v[170:173], v[186:189], v[34:37]
	v_mfma_f32_16x16x32_bf16 v[50:53], v[170:173], v[178:181], v[50:53]
	v_mfma_f32_16x16x32_bf16 v[50:53], v[174:177], v[182:185], v[50:53]
	s_barrier
	s_add_i32 s81, s81, 2
	s_addk_i32 s82, 0x100
	s_cmp_gt_u32 s81, 29
	s_cbranch_scc0 .LBB0_605
	s_andn2_b64 vcc, exec, s[4:5]
	s_cbranch_vccnz .LBB0_597
	v_mov_b32_e32 v2, 0
	s_mov_b32 s42, s77
	s_mov_b32 s3, s78
	s_mov_b32 s59, s10
	s_mov_b32 s64, s9
	s_mov_b32 s75, s8
	v_mov_b32_e32 v3, v2
	v_mov_b32_e32 v4, v2
	v_mov_b32_e32 v5, v2
	v_mov_b32_e32 v6, v2
	v_mov_b32_e32 v7, v2
	v_mov_b32_e32 v8, v2
	v_mov_b32_e32 v9, v2
	v_mov_b32_e32 v18, v2
	v_mov_b32_e32 v19, v2
	v_mov_b32_e32 v20, v2
	v_mov_b32_e32 v21, v2
	v_mov_b32_e32 v22, v2
	v_mov_b32_e32 v23, v2
	v_mov_b32_e32 v24, v2
	v_mov_b32_e32 v25, v2
	v_mov_b32_e32 v34, v2
	v_mov_b32_e32 v35, v2
	v_mov_b32_e32 v36, v2
	v_mov_b32_e32 v37, v2
	v_mov_b32_e32 v38, v2
	v_mov_b32_e32 v39, v2
	v_mov_b32_e32 v40, v2
	v_mov_b32_e32 v41, v2
	v_mov_b32_e32 v50, v2
	v_mov_b32_e32 v51, v2
	v_mov_b32_e32 v52, v2
	v_mov_b32_e32 v53, v2
	v_mov_b32_e32 v54, v2
	v_mov_b32_e32 v55, v2
	v_mov_b32_e32 v56, v2
	v_mov_b32_e32 v57, v2
	v_mov_b32_e32 v10, v2
	v_mov_b32_e32 v11, v2
	v_mov_b32_e32 v12, v2
	v_mov_b32_e32 v13, v2
	v_mov_b32_e32 v14, v2
	v_mov_b32_e32 v15, v2
	v_mov_b32_e32 v16, v2
	v_mov_b32_e32 v17, v2
	v_mov_b32_e32 v26, v2
	v_mov_b32_e32 v27, v2
	v_mov_b32_e32 v28, v2
	v_mov_b32_e32 v29, v2
	v_mov_b32_e32 v30, v2
	v_mov_b32_e32 v31, v2
	v_mov_b32_e32 v32, v2
	v_mov_b32_e32 v33, v2
	v_mov_b32_e32 v42, v2
	v_mov_b32_e32 v43, v2
	v_mov_b32_e32 v44, v2
	v_mov_b32_e32 v45, v2
	v_mov_b32_e32 v46, v2
	v_mov_b32_e32 v47, v2
	v_mov_b32_e32 v48, v2
	v_mov_b32_e32 v49, v2
	v_mov_b32_e32 v58, v2
	v_mov_b32_e32 v59, v2
	v_mov_b32_e32 v60, v2
	v_mov_b32_e32 v61, v2
	v_mov_b32_e32 v62, v2
	v_mov_b32_e32 v63, v2
	v_mov_b32_e32 v64, v2
	v_mov_b32_e32 v65, v2
	v_mov_b32_e32 v66, v2
	v_mov_b32_e32 v67, v2
	v_mov_b32_e32 v68, v2
	v_mov_b32_e32 v69, v2
	v_mov_b32_e32 v70, v2
	v_mov_b32_e32 v71, v2
	v_mov_b32_e32 v72, v2
	v_mov_b32_e32 v73, v2
	v_mov_b32_e32 v82, v2
	v_mov_b32_e32 v83, v2
	v_mov_b32_e32 v84, v2
	v_mov_b32_e32 v85, v2
	v_mov_b32_e32 v86, v2
	v_mov_b32_e32 v87, v2
	v_mov_b32_e32 v88, v2
	v_mov_b32_e32 v89, v2
	v_mov_b32_e32 v98, v2
	v_mov_b32_e32 v99, v2
	v_mov_b32_e32 v100, v2
	v_mov_b32_e32 v101, v2
	v_mov_b32_e32 v102, v2
	v_mov_b32_e32 v103, v2
	v_mov_b32_e32 v104, v2
	v_mov_b32_e32 v105, v2
	v_mov_b32_e32 v114, v2
	v_mov_b32_e32 v115, v2
	v_mov_b32_e32 v116, v2
	v_mov_b32_e32 v117, v2
	v_mov_b32_e32 v118, v2
	v_mov_b32_e32 v119, v2
	v_mov_b32_e32 v120, v2
	v_mov_b32_e32 v121, v2
	v_mov_b32_e32 v74, v2
	v_mov_b32_e32 v75, v2
	v_mov_b32_e32 v76, v2
	v_mov_b32_e32 v77, v2
	v_mov_b32_e32 v78, v2
	v_mov_b32_e32 v79, v2
	v_mov_b32_e32 v80, v2
	v_mov_b32_e32 v81, v2
	v_mov_b32_e32 v90, v2
	v_mov_b32_e32 v91, v2
	v_mov_b32_e32 v92, v2
	v_mov_b32_e32 v93, v2
	v_mov_b32_e32 v94, v2
	v_mov_b32_e32 v95, v2
	v_mov_b32_e32 v96, v2
	v_mov_b32_e32 v97, v2
	v_mov_b32_e32 v106, v2
	v_mov_b32_e32 v107, v2
	v_mov_b32_e32 v108, v2
	v_mov_b32_e32 v109, v2
	v_mov_b32_e32 v110, v2
	v_mov_b32_e32 v111, v2
	v_mov_b32_e32 v112, v2
	v_mov_b32_e32 v113, v2
	v_mov_b32_e32 v122, v2
	v_mov_b32_e32 v123, v2
	v_mov_b32_e32 v124, v2
	v_mov_b32_e32 v125, v2
	v_mov_b32_e32 v126, v2
	v_mov_b32_e32 v127, v2
	v_mov_b32_e32 v128, v2
	v_mov_b32_e32 v129, v2
	s_branch .LBB0_597

.LBB0_822:
	ds_read_b128 v[66:69], v242
	ds_read_b128 v[70:73], v242 offset:1024
	ds_read_b128 v[74:77], v242 offset:2048
	ds_read_b128 v[78:81], v242 offset:3072
	ds_read_b128 v[82:85], v243
	ds_read_b128 v[86:89], v243 offset:1024
	ds_read_b128 v[90:93], v243 offset:2048
	ds_read_b128 v[94:97], v243 offset:3072
	s_add_i32 s43, s68, 0xfff80080
	s_cmp_eq_u32 s69, 28
	s_cselect_b32 s91, s11, s67
	s_cselect_b32 s92, s10, s43
	s_add_i32 s43, s68, 0xfff80000
	s_mov_b32 m0, s79
	ds_read_b128 v[98:101], v244
	ds_read_b128 v[102:105], v244 offset:1024
	buffer_load_dwordx4 v1, s[48:51], s43 offen lds
	s_mov_b32 m0, s80
	ds_read_b128 v[106:109], v244 offset:2048
	ds_read_b128 v[110:113], v244 offset:3072
	buffer_load_dwordx4 v236, s[48:51], s43 offen lds
	s_mov_b32 m0, s81
	ds_read_b128 v[114:117], v244 offset:4096
	ds_read_b128 v[118:121], v244 offset:5120
	buffer_load_dwordx4 v1, s[48:51], s68 offen lds
	s_mov_b32 m0, s82
	ds_read_b128 v[122:125], v244 offset:6144
	ds_read_b128 v[126:129], v244 offset:7168
	buffer_load_dwordx4 v236, s[48:51], s68 offen lds
	s_waitcnt vmcnt(8)
	s_waitcnt lgkmcnt(0)
	s_barrier
	s_waitcnt lgkmcnt(0)
	v_mfma_f32_16x16x32_bf16 v[190:193], v[66:69], v[98:101], v[190:193]
	v_mfma_f32_16x16x32_bf16 v[190:193], v[70:73], v[102:105], v[190:193]
	v_mfma_f32_16x16x32_bf16 v[174:177], v[70:73], v[110:113], v[174:177]
	v_mfma_f32_16x16x32_bf16 v[174:177], v[66:69], v[106:109], v[174:177]
	v_mfma_f32_16x16x32_bf16 v[170:173], v[66:69], v[114:117], v[170:173]
	v_mfma_f32_16x16x32_bf16 v[170:173], v[70:73], v[118:121], v[170:173]
	v_mfma_f32_16x16x32_bf16 v[158:161], v[70:73], v[126:129], v[158:161]
	v_mfma_f32_16x16x32_bf16 v[158:161], v[66:69], v[122:125], v[158:161]
	v_mfma_f32_16x16x32_bf16 v[154:157], v[78:81], v[126:129], v[154:157]
	v_mfma_f32_16x16x32_bf16 v[154:157], v[74:77], v[122:125], v[154:157]
	v_mfma_f32_16x16x32_bf16 v[162:165], v[74:77], v[114:117], v[162:165]
	v_mfma_f32_16x16x32_bf16 v[162:165], v[78:81], v[118:121], v[162:165]
	v_mfma_f32_16x16x32_bf16 v[166:169], v[78:81], v[110:113], v[166:169]
	v_mfma_f32_16x16x32_bf16 v[166:169], v[74:77], v[106:109], v[166:169]
	v_mfma_f32_16x16x32_bf16 v[186:189], v[74:77], v[98:101], v[186:189]
	v_mfma_f32_16x16x32_bf16 v[186:189], v[78:81], v[102:105], v[186:189]
	v_mfma_f32_16x16x32_bf16 v[182:185], v[82:85], v[98:101], v[182:185]
	v_mfma_f32_16x16x32_bf16 v[182:185], v[86:89], v[102:105], v[182:185]
	v_mfma_f32_16x16x32_bf16 v[98:101], v[90:93], v[98:101], v[178:181]
	v_mfma_f32_16x16x32_bf16 v[98:101], v[94:97], v[102:105], v[98:101]
	v_mfma_f32_16x16x32_bf16 v[102:105], v[82:85], v[106:109], v[150:153]
	v_mfma_f32_16x16x32_bf16 v[102:105], v[86:89], v[110:113], v[102:105]
	v_mfma_f32_16x16x32_bf16 v[106:109], v[90:93], v[106:109], v[142:145]
	v_mfma_f32_16x16x32_bf16 v[106:109], v[94:97], v[110:113], v[106:109]
	v_mfma_f32_16x16x32_bf16 v[110:113], v[82:85], v[114:117], v[146:149]
	v_mfma_f32_16x16x32_bf16 v[110:113], v[86:89], v[118:121], v[110:113]
	v_mfma_f32_16x16x32_bf16 v[114:117], v[90:93], v[114:117], v[138:141]
	v_mfma_f32_16x16x32_bf16 v[114:117], v[94:97], v[118:121], v[114:117]
	v_mfma_f32_16x16x32_bf16 v[118:121], v[82:85], v[122:125], v[134:137]
	v_mfma_f32_16x16x32_bf16 v[118:121], v[86:89], v[126:129], v[118:121]
	v_mfma_f32_16x16x32_bf16 v[122:125], v[90:93], v[122:125], v[130:133]
	v_mfma_f32_16x16x32_bf16 v[122:125], v[94:97], v[126:129], v[122:125]
	s_barrier
	s_mov_b32 m0, s29
	s_mov_b32 s43, s51
	ds_read_b128 v[126:129], v244 offset:16384
	ds_read_b128 v[130:133], v244 offset:17408
	buffer_load_dwordx4 v227, s[40:43], s91 offen lds
	s_mov_b32 m0, s35
	ds_read_b128 v[134:137], v244 offset:18432
	ds_read_b128 v[138:141], v244 offset:19456
	buffer_load_dwordx4 v237, s[40:43], s91 offen lds
	s_add_i32 s93, s91, 0x1600000
	s_mov_b32 m0, s63
	ds_read_b128 v[142:145], v244 offset:20480
	ds_read_b128 v[146:149], v244 offset:21504
	buffer_load_dwordx4 v227, s[40:43], s93 offen lds
	s_mov_b32 m0, s65
	ds_read_b128 v[150:153], v244 offset:22528
	ds_read_b128 v[178:181], v244 offset:23552
	buffer_load_dwordx4 v237, s[40:43], s93 offen lds
	s_waitcnt vmcnt(6)
	s_waitcnt lgkmcnt(0)
	s_barrier
	s_waitcnt lgkmcnt(0)
	v_mfma_f32_16x16x32_bf16 v[62:65], v[66:69], v[126:129], v[62:65]
	v_mfma_f32_16x16x32_bf16 v[62:65], v[70:73], v[130:133], v[62:65]
	v_mfma_f32_16x16x32_bf16 v[46:49], v[70:73], v[138:141], v[46:49]
	v_mfma_f32_16x16x32_bf16 v[46:49], v[66:69], v[134:137], v[46:49]
	v_mfma_f32_16x16x32_bf16 v[42:45], v[66:69], v[142:145], v[42:45]
	v_mfma_f32_16x16x32_bf16 v[42:45], v[70:73], v[146:149], v[42:45]
	v_mfma_f32_16x16x32_bf16 v[30:33], v[70:73], v[178:181], v[30:33]
	v_mfma_f32_16x16x32_bf16 v[30:33], v[66:69], v[150:153], v[30:33]
	v_mfma_f32_16x16x32_bf16 v[26:29], v[78:81], v[178:181], v[26:29]
	v_mfma_f32_16x16x32_bf16 v[26:29], v[74:77], v[150:153], v[26:29]
	v_mfma_f32_16x16x32_bf16 v[34:37], v[74:77], v[142:145], v[34:37]
	v_mfma_f32_16x16x32_bf16 v[34:37], v[78:81], v[146:149], v[34:37]
	v_mfma_f32_16x16x32_bf16 v[38:41], v[78:81], v[138:141], v[38:41]
	v_mfma_f32_16x16x32_bf16 v[38:41], v[74:77], v[134:137], v[38:41]
	v_mfma_f32_16x16x32_bf16 v[58:61], v[74:77], v[126:129], v[58:61]
	v_mfma_f32_16x16x32_bf16 v[58:61], v[78:81], v[130:133], v[58:61]
	v_mfma_f32_16x16x32_bf16 v[54:57], v[82:85], v[126:129], v[54:57]
	v_mfma_f32_16x16x32_bf16 v[54:57], v[86:89], v[130:133], v[54:57]
	v_mfma_f32_16x16x32_bf16 v[22:25], v[86:89], v[138:141], v[22:25]
	v_mfma_f32_16x16x32_bf16 v[22:25], v[82:85], v[134:137], v[22:25]
	v_mfma_f32_16x16x32_bf16 v[18:21], v[82:85], v[142:145], v[18:21]
	v_mfma_f32_16x16x32_bf16 v[18:21], v[86:89], v[146:149], v[18:21]
	v_mfma_f32_16x16x32_bf16 v[6:9], v[86:89], v[178:181], v[6:9]
	v_mfma_f32_16x16x32_bf16 v[6:9], v[82:85], v[150:153], v[6:9]
	v_mfma_f32_16x16x32_bf16 v[2:5], v[94:97], v[178:181], v[2:5]
	v_mfma_f32_16x16x32_bf16 v[2:5], v[90:93], v[150:153], v[2:5]
	v_mfma_f32_16x16x32_bf16 v[10:13], v[90:93], v[142:145], v[10:13]
	v_mfma_f32_16x16x32_bf16 v[10:13], v[94:97], v[146:149], v[10:13]
	v_mfma_f32_16x16x32_bf16 v[14:17], v[94:97], v[138:141], v[14:17]
	v_mfma_f32_16x16x32_bf16 v[14:17], v[90:93], v[134:137], v[14:17]
	v_mfma_f32_16x16x32_bf16 v[50:53], v[90:93], v[126:129], v[50:53]
	v_mfma_f32_16x16x32_bf16 v[50:53], v[94:97], v[130:133], v[50:53]
	s_barrier
	ds_read_b128 v[66:69], v245
	ds_read_b128 v[70:73], v245 offset:1024
	ds_read_b128 v[74:77], v245 offset:2048
	ds_read_b128 v[78:81], v245 offset:3072
	ds_read_b128 v[82:85], v246
	ds_read_b128 v[86:89], v246 offset:1024
	ds_read_b128 v[90:93], v246 offset:2048
	ds_read_b128 v[94:97], v246 offset:3072
	s_mov_b32 m0, s3
	ds_read_b128 v[126:129], v244 offset:32768
	ds_read_b128 v[130:133], v244 offset:33792
	buffer_load_dwordx4 v1, s[48:51], s92 offen lds
	s_mov_b32 m0, s70
	ds_read_b128 v[134:137], v244 offset:34816
	ds_read_b128 v[138:141], v244 offset:35840
	buffer_load_dwordx4 v236, s[48:51], s92 offen lds
	s_add_i32 s92, s92, 0x80000
	s_mov_b32 m0, s71
	ds_read_b128 v[194:197], v244 offset:36864
	ds_read_b128 v[198:201], v244 offset:37888
	buffer_load_dwordx4 v1, s[48:51], s92 offen lds
	s_mov_b32 m0, s72
	ds_read_b128 v[202:205], v244 offset:38912
	ds_read_b128 v[206:209], v244 offset:39936
	buffer_load_dwordx4 v236, s[48:51], s92 offen lds
	s_waitcnt vmcnt(8)
	s_waitcnt lgkmcnt(0)
	s_barrier
	s_waitcnt lgkmcnt(0)
	v_mfma_f32_16x16x32_bf16 v[142:145], v[66:69], v[126:129], v[190:193]
	v_mfma_f32_16x16x32_bf16 v[190:193], v[70:73], v[130:133], v[142:145]
	v_mfma_f32_16x16x32_bf16 v[142:145], v[74:77], v[126:129], v[186:189]
	v_mfma_f32_16x16x32_bf16 v[186:189], v[78:81], v[130:133], v[142:145]
	v_mfma_f32_16x16x32_bf16 v[142:145], v[66:69], v[134:137], v[174:177]
	v_mfma_f32_16x16x32_bf16 v[174:177], v[70:73], v[138:141], v[142:145]
	v_mfma_f32_16x16x32_bf16 v[142:145], v[74:77], v[134:137], v[166:169]
	v_mfma_f32_16x16x32_bf16 v[166:169], v[78:81], v[138:141], v[142:145]
	v_mfma_f32_16x16x32_bf16 v[142:145], v[66:69], v[194:197], v[170:173]
	v_mfma_f32_16x16x32_bf16 v[170:173], v[70:73], v[198:201], v[142:145]
	v_mfma_f32_16x16x32_bf16 v[142:145], v[74:77], v[194:197], v[162:165]
	v_mfma_f32_16x16x32_bf16 v[162:165], v[78:81], v[198:201], v[142:145]
	v_mfma_f32_16x16x32_bf16 v[142:145], v[66:69], v[202:205], v[158:161]
	v_mfma_f32_16x16x32_bf16 v[158:161], v[70:73], v[206:209], v[142:145]
	v_mfma_f32_16x16x32_bf16 v[142:145], v[74:77], v[202:205], v[154:157]
	v_mfma_f32_16x16x32_bf16 v[154:157], v[78:81], v[206:209], v[142:145]
	v_mfma_f32_16x16x32_bf16 v[98:101], v[90:93], v[126:129], v[98:101]
	v_mfma_f32_16x16x32_bf16 v[178:181], v[94:97], v[130:133], v[98:101]
	v_mfma_f32_16x16x32_bf16 v[142:145], v[82:85], v[126:129], v[182:185]
	v_mfma_f32_16x16x32_bf16 v[182:185], v[86:89], v[130:133], v[142:145]
	v_mfma_f32_16x16x32_bf16 v[98:101], v[82:85], v[134:137], v[102:105]
	v_mfma_f32_16x16x32_bf16 v[150:153], v[86:89], v[138:141], v[98:101]
	v_mfma_f32_16x16x32_bf16 v[98:101], v[90:93], v[134:137], v[106:109]
	v_mfma_f32_16x16x32_bf16 v[142:145], v[94:97], v[138:141], v[98:101]
	v_mfma_f32_16x16x32_bf16 v[98:101], v[82:85], v[194:197], v[110:113]
	v_mfma_f32_16x16x32_bf16 v[146:149], v[86:89], v[198:201], v[98:101]
	v_mfma_f32_16x16x32_bf16 v[98:101], v[90:93], v[194:197], v[114:117]
	v_mfma_f32_16x16x32_bf16 v[138:141], v[94:97], v[198:201], v[98:101]
	v_mfma_f32_16x16x32_bf16 v[98:101], v[82:85], v[202:205], v[118:121]
	v_mfma_f32_16x16x32_bf16 v[134:137], v[86:89], v[206:209], v[98:101]
	v_mfma_f32_16x16x32_bf16 v[98:101], v[90:93], v[202:205], v[122:125]
	v_mfma_f32_16x16x32_bf16 v[130:133], v[94:97], v[206:209], v[98:101]
	s_barrier
	s_mov_b32 m0, s74
	s_or_b32 s92, s91, 0x80
	s_nop 2
	ds_read_b128 v[98:101], v244 offset:49152
	ds_read_b128 v[102:105], v244 offset:50176
	buffer_load_dwordx4 v227, s[40:43], s92 offen lds
	s_mov_b32 m0, s75
	ds_read_b128 v[106:109], v244 offset:51200
	ds_read_b128 v[110:113], v244 offset:52224
	buffer_load_dwordx4 v237, s[40:43], s92 offen lds
	s_add_i32 s91, s91, 0x1600080
	s_mov_b32 m0, s77
	ds_read_b128 v[114:117], v244 offset:53248
	ds_read_b128 v[118:121], v244 offset:54272
	buffer_load_dwordx4 v227, s[40:43], s91 offen lds
	s_mov_b32 m0, s78
	ds_read_b128 v[122:125], v244 offset:55296
	ds_read_b128 v[126:129], v244 offset:56320
	buffer_load_dwordx4 v237, s[40:43], s91 offen lds
	s_waitcnt vmcnt(6)
	s_waitcnt lgkmcnt(0)
	s_barrier
	s_waitcnt lgkmcnt(0)
	v_mfma_f32_16x16x32_bf16 v[62:65], v[66:69], v[98:101], v[62:65]
	v_mfma_f32_16x16x32_bf16 v[62:65], v[70:73], v[102:105], v[62:65]
	v_mfma_f32_16x16x32_bf16 v[46:49], v[70:73], v[110:113], v[46:49]
	v_mfma_f32_16x16x32_bf16 v[46:49], v[66:69], v[106:109], v[46:49]
	v_mfma_f32_16x16x32_bf16 v[42:45], v[66:69], v[114:117], v[42:45]
	v_mfma_f32_16x16x32_bf16 v[42:45], v[70:73], v[118:121], v[42:45]
	v_mfma_f32_16x16x32_bf16 v[30:33], v[70:73], v[126:129], v[30:33]
	v_mfma_f32_16x16x32_bf16 v[30:33], v[66:69], v[122:125], v[30:33]
	v_mfma_f32_16x16x32_bf16 v[26:29], v[78:81], v[126:129], v[26:29]
	v_mfma_f32_16x16x32_bf16 v[26:29], v[74:77], v[122:125], v[26:29]
	v_mfma_f32_16x16x32_bf16 v[34:37], v[74:77], v[114:117], v[34:37]
	v_mfma_f32_16x16x32_bf16 v[34:37], v[78:81], v[118:121], v[34:37]
	v_mfma_f32_16x16x32_bf16 v[38:41], v[78:81], v[110:113], v[38:41]
	v_mfma_f32_16x16x32_bf16 v[38:41], v[74:77], v[106:109], v[38:41]
	v_mfma_f32_16x16x32_bf16 v[58:61], v[74:77], v[98:101], v[58:61]
	v_mfma_f32_16x16x32_bf16 v[58:61], v[78:81], v[102:105], v[58:61]
	v_mfma_f32_16x16x32_bf16 v[54:57], v[82:85], v[98:101], v[54:57]
	v_mfma_f32_16x16x32_bf16 v[54:57], v[86:89], v[102:105], v[54:57]
	v_mfma_f32_16x16x32_bf16 v[22:25], v[86:89], v[110:113], v[22:25]
	v_mfma_f32_16x16x32_bf16 v[22:25], v[82:85], v[106:109], v[22:25]
	v_mfma_f32_16x16x32_bf16 v[18:21], v[82:85], v[114:117], v[18:21]
	v_mfma_f32_16x16x32_bf16 v[18:21], v[86:89], v[118:121], v[18:21]
	v_mfma_f32_16x16x32_bf16 v[6:9], v[86:89], v[126:129], v[6:9]
	v_mfma_f32_16x16x32_bf16 v[6:9], v[82:85], v[122:125], v[6:9]
	v_mfma_f32_16x16x32_bf16 v[2:5], v[94:97], v[126:129], v[2:5]
	v_mfma_f32_16x16x32_bf16 v[2:5], v[90:93], v[122:125], v[2:5]
	v_mfma_f32_16x16x32_bf16 v[10:13], v[90:93], v[114:117], v[10:13]
	v_mfma_f32_16x16x32_bf16 v[10:13], v[94:97], v[118:121], v[10:13]
	v_mfma_f32_16x16x32_bf16 v[14:17], v[94:97], v[110:113], v[14:17]
	v_mfma_f32_16x16x32_bf16 v[14:17], v[90:93], v[106:109], v[14:17]
	v_mfma_f32_16x16x32_bf16 v[50:53], v[90:93], v[98:101], v[50:53]
	v_mfma_f32_16x16x32_bf16 v[50:53], v[94:97], v[102:105], v[50:53]
	s_barrier
	s_add_i32 s69, s69, 2
	s_addk_i32 s67, 0x100
	s_addk_i32 s68, 0x100
	s_cmp_gt_u32 s69, 29
	s_cbranch_scc0 .LBB0_822
	s_and_b64 vcc, exec, s[38:39]
	s_cbranch_vccz .LBB0_825
	s_barrier

.LBB0_1003:
	v_add_u32_e32 v130, 0x10000, v155
	ds_read_b128 v[132:135], v130
	ds_read_b128 v[144:147], v130 offset:1024
	ds_read_b128 v[158:161], v130 offset:2048
	ds_read_b128 v[162:165], v130 offset:3072
	v_add_u32_e32 v130, 0x14000, v155
	s_lshl_b32 s39, s92, 7
	ds_read_b128 v[166:169], v130
	ds_read_b128 v[170:173], v130 offset:1024
	ds_read_b128 v[174:177], v130 offset:2048
	ds_read_b128 v[178:181], v130 offset:3072
	s_add_i32 s93, s61, s39
	s_addk_i32 s39, 0x100
	s_add_i32 s94, s93, 0x80
	s_add_i32 s95, s39, s61
	s_and_b64 s[50:51], s[48:49], exec
	s_cselect_b32 s50, s87, s95
	s_add_i32 s39, s39, s63
	s_and_b64 s[48:49], s[48:49], exec
	s_cselect_b32 s48, s88, s39
	s_or_b32 s49, s48, 0x80
	s_mov_b32 m0, s77
	ds_read_b128 v[182:185], v156
	ds_read_b128 v[186:189], v156 offset:1024
	buffer_load_dwordx4 v151, s[28:31], s94 offen lds
	s_mov_b32 m0, s78
	ds_read_b128 v[190:193], v156 offset:2048
	ds_read_b128 v[194:197], v156 offset:3072
	buffer_load_dwordx4 v153, s[28:31], s94 offen lds
	s_add_i32 s93, s93, 0x160080
	s_mov_b32 m0, s79
	ds_read_b128 v[198:201], v156 offset:4096
	ds_read_b128 v[202:205], v156 offset:5120
	buffer_load_dwordx4 v151, s[28:31], s93 offen lds
	s_mov_b32 m0, s80
	ds_read_b128 v[206:209], v156 offset:6144
	ds_read_b128 v[210:213], v156 offset:7168
	buffer_load_dwordx4 v153, s[28:31], s93 offen lds
	s_waitcnt vmcnt(8)
	s_waitcnt lgkmcnt(0)
	s_barrier
	s_waitcnt lgkmcnt(0)
	v_mfma_f32_16x16x32_bf16 v[126:129], v[132:135], v[182:185], v[126:129]
	v_mfma_f32_16x16x32_bf16 v[126:129], v[144:147], v[186:189], v[126:129]
	v_mfma_f32_16x16x32_bf16 v[110:113], v[144:147], v[194:197], v[110:113]
	v_mfma_f32_16x16x32_bf16 v[110:113], v[132:135], v[190:193], v[110:113]
	v_mfma_f32_16x16x32_bf16 v[94:97], v[132:135], v[198:201], v[94:97]
	v_mfma_f32_16x16x32_bf16 v[94:97], v[144:147], v[202:205], v[94:97]
	v_mfma_f32_16x16x32_bf16 v[78:81], v[144:147], v[210:213], v[78:81]
	v_mfma_f32_16x16x32_bf16 v[78:81], v[132:135], v[206:209], v[78:81]
	v_mfma_f32_16x16x32_bf16 v[74:77], v[162:165], v[210:213], v[74:77]
	v_mfma_f32_16x16x32_bf16 v[74:77], v[158:161], v[206:209], v[74:77]
	v_mfma_f32_16x16x32_bf16 v[90:93], v[158:161], v[198:201], v[90:93]
	v_mfma_f32_16x16x32_bf16 v[90:93], v[162:165], v[202:205], v[90:93]
	v_mfma_f32_16x16x32_bf16 v[106:109], v[162:165], v[194:197], v[106:109]
	v_mfma_f32_16x16x32_bf16 v[106:109], v[158:161], v[190:193], v[106:109]
	v_mfma_f32_16x16x32_bf16 v[122:125], v[158:161], v[182:185], v[122:125]
	v_mfma_f32_16x16x32_bf16 v[122:125], v[162:165], v[186:189], v[122:125]
	v_mfma_f32_16x16x32_bf16 v[118:121], v[166:169], v[182:185], v[118:121]
	v_mfma_f32_16x16x32_bf16 v[118:121], v[170:173], v[186:189], v[118:121]
	v_mfma_f32_16x16x32_bf16 v[102:105], v[170:173], v[194:197], v[102:105]
	v_mfma_f32_16x16x32_bf16 v[102:105], v[166:169], v[190:193], v[102:105]
	v_mfma_f32_16x16x32_bf16 v[86:89], v[166:169], v[198:201], v[86:89]
	v_mfma_f32_16x16x32_bf16 v[86:89], v[170:173], v[202:205], v[86:89]
	v_mfma_f32_16x16x32_bf16 v[70:73], v[170:173], v[210:213], v[70:73]
	v_mfma_f32_16x16x32_bf16 v[70:73], v[166:169], v[206:209], v[70:73]
	v_mfma_f32_16x16x32_bf16 v[66:69], v[178:181], v[210:213], v[66:69]
	v_mfma_f32_16x16x32_bf16 v[66:69], v[174:177], v[206:209], v[66:69]
	v_mfma_f32_16x16x32_bf16 v[82:85], v[174:177], v[198:201], v[82:85]
	v_mfma_f32_16x16x32_bf16 v[82:85], v[178:181], v[202:205], v[82:85]
	v_mfma_f32_16x16x32_bf16 v[98:101], v[178:181], v[194:197], v[98:101]
	v_mfma_f32_16x16x32_bf16 v[98:101], v[174:177], v[190:193], v[98:101]
	v_mfma_f32_16x16x32_bf16 v[114:117], v[174:177], v[182:185], v[114:117]
	v_mfma_f32_16x16x32_bf16 v[114:117], v[178:181], v[186:189], v[114:117]
	s_barrier
	s_mov_b32 m0, s64
	s_mov_b32 s39, s31
	ds_read_b128 v[182:185], v156 offset:16384
	ds_read_b128 v[186:189], v156 offset:17408
	buffer_load_dwordx4 v152, s[36:39], s48 offen lds
	s_mov_b32 m0, s65
	ds_read_b128 v[190:193], v156 offset:18432
	ds_read_b128 v[194:197], v156 offset:19456
	buffer_load_dwordx4 v154, s[36:39], s48 offen lds
	s_add_i32 s51, s48, 0x160000
	s_mov_b32 m0, s66
	ds_read_b128 v[198:201], v156 offset:20480
	ds_read_b128 v[202:205], v156 offset:21504
	buffer_load_dwordx4 v152, s[36:39], s51 offen lds
	s_mov_b32 m0, s67
	ds_read_b128 v[206:209], v156 offset:22528
	ds_read_b128 v[210:213], v156 offset:23552
	buffer_load_dwordx4 v154, s[36:39], s51 offen lds
	s_waitcnt vmcnt(6)
	s_waitcnt lgkmcnt(0)
	s_barrier
	s_waitcnt lgkmcnt(0)
	v_mfma_f32_16x16x32_bf16 v[62:65], v[132:135], v[182:185], v[62:65]
	v_mfma_f32_16x16x32_bf16 v[62:65], v[144:147], v[186:189], v[62:65]
	v_mfma_f32_16x16x32_bf16 v[46:49], v[144:147], v[194:197], v[46:49]
	v_mfma_f32_16x16x32_bf16 v[46:49], v[132:135], v[190:193], v[46:49]
	v_mfma_f32_16x16x32_bf16 v[30:33], v[132:135], v[198:201], v[30:33]
	v_mfma_f32_16x16x32_bf16 v[30:33], v[144:147], v[202:205], v[30:33]
	v_mfma_f32_16x16x32_bf16 v[14:17], v[144:147], v[210:213], v[14:17]
	v_mfma_f32_16x16x32_bf16 v[14:17], v[132:135], v[206:209], v[14:17]
	v_mfma_f32_16x16x32_bf16 v[10:13], v[162:165], v[210:213], v[10:13]
	v_mfma_f32_16x16x32_bf16 v[10:13], v[158:161], v[206:209], v[10:13]
	v_mfma_f32_16x16x32_bf16 v[26:29], v[158:161], v[198:201], v[26:29]
	v_mfma_f32_16x16x32_bf16 v[26:29], v[162:165], v[202:205], v[26:29]
	v_mfma_f32_16x16x32_bf16 v[42:45], v[162:165], v[194:197], v[42:45]
	v_mfma_f32_16x16x32_bf16 v[42:45], v[158:161], v[190:193], v[42:45]
	v_mfma_f32_16x16x32_bf16 v[58:61], v[158:161], v[182:185], v[58:61]
	v_mfma_f32_16x16x32_bf16 v[58:61], v[162:165], v[186:189], v[58:61]
	v_mfma_f32_16x16x32_bf16 v[54:57], v[166:169], v[182:185], v[54:57]
	v_mfma_f32_16x16x32_bf16 v[54:57], v[170:173], v[186:189], v[54:57]
	v_mfma_f32_16x16x32_bf16 v[38:41], v[170:173], v[194:197], v[38:41]
	v_mfma_f32_16x16x32_bf16 v[38:41], v[166:169], v[190:193], v[38:41]
	v_mfma_f32_16x16x32_bf16 v[22:25], v[166:169], v[198:201], v[22:25]
	v_mfma_f32_16x16x32_bf16 v[22:25], v[170:173], v[202:205], v[22:25]
	v_mfma_f32_16x16x32_bf16 v[6:9], v[170:173], v[210:213], v[6:9]
	v_mfma_f32_16x16x32_bf16 v[6:9], v[166:169], v[206:209], v[6:9]
	v_mfma_f32_16x16x32_bf16 v[2:5], v[178:181], v[210:213], v[2:5]
	v_mfma_f32_16x16x32_bf16 v[2:5], v[174:177], v[206:209], v[2:5]
	v_mfma_f32_16x16x32_bf16 v[18:21], v[174:177], v[198:201], v[18:21]
	v_mfma_f32_16x16x32_bf16 v[18:21], v[178:181], v[202:205], v[18:21]
	v_mfma_f32_16x16x32_bf16 v[34:37], v[178:181], v[194:197], v[34:37]
	v_mfma_f32_16x16x32_bf16 v[34:37], v[174:177], v[190:193], v[34:37]
	v_mfma_f32_16x16x32_bf16 v[50:53], v[174:177], v[182:185], v[50:53]
	v_mfma_f32_16x16x32_bf16 v[50:53], v[178:181], v[186:189], v[50:53]
	s_barrier
	v_add_u32_e32 v130, 0x18000, v155
	ds_read_b128 v[132:135], v130
	ds_read_b128 v[144:147], v130 offset:1024
	ds_read_b128 v[158:161], v130 offset:2048
	ds_read_b128 v[162:165], v130 offset:3072
	v_add_u32_e32 v130, 0x1c000, v155
	ds_read_b128 v[166:169], v130
	ds_read_b128 v[170:173], v130 offset:1024
	ds_read_b128 v[174:177], v130 offset:2048
	ds_read_b128 v[178:181], v130 offset:3072
	s_mov_b32 m0, s62
	ds_read_b128 v[182:185], v156 offset:32768
	ds_read_b128 v[186:189], v156 offset:33792
	buffer_load_dwordx4 v151, s[28:31], s50 offen lds
	s_mov_b32 m0, s68
	ds_read_b128 v[190:193], v156 offset:34816
	ds_read_b128 v[194:197], v156 offset:35840
	buffer_load_dwordx4 v153, s[28:31], s50 offen lds
	s_add_i32 s50, s50, 0x160000
	s_mov_b32 m0, s69
	ds_read_b128 v[198:201], v156 offset:36864
	ds_read_b128 v[202:205], v156 offset:37888
	buffer_load_dwordx4 v151, s[28:31], s50 offen lds
	s_mov_b32 m0, s70
	ds_read_b128 v[206:209], v156 offset:38912
	ds_read_b128 v[210:213], v156 offset:39936
	buffer_load_dwordx4 v153, s[28:31], s50 offen lds
	s_waitcnt vmcnt(8)
	s_waitcnt lgkmcnt(0)
	s_barrier
	s_waitcnt lgkmcnt(0)
	v_mfma_f32_16x16x32_bf16 v[126:129], v[132:135], v[182:185], v[126:129]
	v_mfma_f32_16x16x32_bf16 v[126:129], v[144:147], v[186:189], v[126:129]
	v_mfma_f32_16x16x32_bf16 v[110:113], v[144:147], v[194:197], v[110:113]
	v_mfma_f32_16x16x32_bf16 v[110:113], v[132:135], v[190:193], v[110:113]
	v_mfma_f32_16x16x32_bf16 v[94:97], v[132:135], v[198:201], v[94:97]
	v_mfma_f32_16x16x32_bf16 v[94:97], v[144:147], v[202:205], v[94:97]
	v_mfma_f32_16x16x32_bf16 v[78:81], v[144:147], v[210:213], v[78:81]
	v_mfma_f32_16x16x32_bf16 v[78:81], v[132:135], v[206:209], v[78:81]
	v_mfma_f32_16x16x32_bf16 v[74:77], v[162:165], v[210:213], v[74:77]
	v_mfma_f32_16x16x32_bf16 v[74:77], v[158:161], v[206:209], v[74:77]
	v_mfma_f32_16x16x32_bf16 v[90:93], v[158:161], v[198:201], v[90:93]
	v_mfma_f32_16x16x32_bf16 v[90:93], v[162:165], v[202:205], v[90:93]
	v_mfma_f32_16x16x32_bf16 v[106:109], v[162:165], v[194:197], v[106:109]
	v_mfma_f32_16x16x32_bf16 v[106:109], v[158:161], v[190:193], v[106:109]
	v_mfma_f32_16x16x32_bf16 v[122:125], v[158:161], v[182:185], v[122:125]
	v_mfma_f32_16x16x32_bf16 v[122:125], v[162:165], v[186:189], v[122:125]
	v_mfma_f32_16x16x32_bf16 v[118:121], v[166:169], v[182:185], v[118:121]
	v_mfma_f32_16x16x32_bf16 v[118:121], v[170:173], v[186:189], v[118:121]
	v_mfma_f32_16x16x32_bf16 v[102:105], v[170:173], v[194:197], v[102:105]
	v_mfma_f32_16x16x32_bf16 v[102:105], v[166:169], v[190:193], v[102:105]
	v_mfma_f32_16x16x32_bf16 v[86:89], v[166:169], v[198:201], v[86:89]
	v_mfma_f32_16x16x32_bf16 v[86:89], v[170:173], v[202:205], v[86:89]
	v_mfma_f32_16x16x32_bf16 v[70:73], v[170:173], v[210:213], v[70:73]
	v_mfma_f32_16x16x32_bf16 v[70:73], v[166:169], v[206:209], v[70:73]
	v_mfma_f32_16x16x32_bf16 v[66:69], v[178:181], v[210:213], v[66:69]
	v_mfma_f32_16x16x32_bf16 v[66:69], v[174:177], v[206:209], v[66:69]
	v_mfma_f32_16x16x32_bf16 v[82:85], v[174:177], v[198:201], v[82:85]
	v_mfma_f32_16x16x32_bf16 v[82:85], v[178:181], v[202:205], v[82:85]
	v_mfma_f32_16x16x32_bf16 v[98:101], v[178:181], v[194:197], v[98:101]
	v_mfma_f32_16x16x32_bf16 v[98:101], v[174:177], v[190:193], v[98:101]
	v_mfma_f32_16x16x32_bf16 v[114:117], v[174:177], v[182:185], v[114:117]
	v_mfma_f32_16x16x32_bf16 v[114:117], v[178:181], v[186:189], v[114:117]
	s_barrier
	s_mov_b32 m0, s72
	ds_read_b128 v[182:185], v156 offset:49152
	ds_read_b128 v[186:189], v156 offset:50176
	buffer_load_dwordx4 v152, s[36:39], s49 offen lds
	s_mov_b32 m0, s73
	ds_read_b128 v[190:193], v156 offset:51200
	ds_read_b128 v[194:197], v156 offset:52224
	buffer_load_dwordx4 v154, s[36:39], s49 offen lds
	s_add_i32 s48, s48, 0x160080
	s_mov_b32 m0, s74
	ds_read_b128 v[198:201], v156 offset:53248
	ds_read_b128 v[202:205], v156 offset:54272
	buffer_load_dwordx4 v152, s[36:39], s48 offen lds
	s_mov_b32 m0, s75
	ds_read_b128 v[206:209], v156 offset:55296
	ds_read_b128 v[210:213], v156 offset:56320
	buffer_load_dwordx4 v154, s[36:39], s48 offen lds
	s_waitcnt vmcnt(6)
	s_waitcnt lgkmcnt(0)
	s_barrier
	s_waitcnt lgkmcnt(0)
	v_mfma_f32_16x16x32_bf16 v[62:65], v[132:135], v[182:185], v[62:65]
	v_mfma_f32_16x16x32_bf16 v[62:65], v[144:147], v[186:189], v[62:65]
	v_mfma_f32_16x16x32_bf16 v[46:49], v[144:147], v[194:197], v[46:49]
	v_mfma_f32_16x16x32_bf16 v[46:49], v[132:135], v[190:193], v[46:49]
	v_mfma_f32_16x16x32_bf16 v[30:33], v[132:135], v[198:201], v[30:33]
	v_mfma_f32_16x16x32_bf16 v[30:33], v[144:147], v[202:205], v[30:33]
	v_mfma_f32_16x16x32_bf16 v[14:17], v[144:147], v[210:213], v[14:17]
	v_mfma_f32_16x16x32_bf16 v[14:17], v[132:135], v[206:209], v[14:17]
	v_mfma_f32_16x16x32_bf16 v[10:13], v[162:165], v[210:213], v[10:13]
	v_mfma_f32_16x16x32_bf16 v[10:13], v[158:161], v[206:209], v[10:13]
	v_mfma_f32_16x16x32_bf16 v[26:29], v[158:161], v[198:201], v[26:29]
	v_mfma_f32_16x16x32_bf16 v[26:29], v[162:165], v[202:205], v[26:29]
	v_mfma_f32_16x16x32_bf16 v[42:45], v[162:165], v[194:197], v[42:45]
	v_mfma_f32_16x16x32_bf16 v[42:45], v[158:161], v[190:193], v[42:45]
	v_mfma_f32_16x16x32_bf16 v[58:61], v[158:161], v[182:185], v[58:61]
	v_mfma_f32_16x16x32_bf16 v[58:61], v[162:165], v[186:189], v[58:61]
	v_mfma_f32_16x16x32_bf16 v[54:57], v[166:169], v[182:185], v[54:57]
	v_mfma_f32_16x16x32_bf16 v[54:57], v[170:173], v[186:189], v[54:57]
	v_mfma_f32_16x16x32_bf16 v[38:41], v[170:173], v[194:197], v[38:41]
	v_mfma_f32_16x16x32_bf16 v[38:41], v[166:169], v[190:193], v[38:41]
	v_mfma_f32_16x16x32_bf16 v[22:25], v[166:169], v[198:201], v[22:25]
	v_mfma_f32_16x16x32_bf16 v[22:25], v[170:173], v[202:205], v[22:25]
	v_mfma_f32_16x16x32_bf16 v[6:9], v[170:173], v[210:213], v[6:9]
	v_mfma_f32_16x16x32_bf16 v[6:9], v[166:169], v[206:209], v[6:9]
	v_mfma_f32_16x16x32_bf16 v[2:5], v[178:181], v[210:213], v[2:5]
	v_mfma_f32_16x16x32_bf16 v[2:5], v[174:177], v[206:209], v[2:5]
	v_mfma_f32_16x16x32_bf16 v[18:21], v[174:177], v[198:201], v[18:21]
	v_mfma_f32_16x16x32_bf16 v[18:21], v[178:181], v[202:205], v[18:21]
	v_mfma_f32_16x16x32_bf16 v[34:37], v[178:181], v[194:197], v[34:37]
	v_mfma_f32_16x16x32_bf16 v[34:37], v[174:177], v[190:193], v[34:37]
	v_mfma_f32_16x16x32_bf16 v[50:53], v[174:177], v[182:185], v[50:53]
	v_mfma_f32_16x16x32_bf16 v[50:53], v[178:181], v[186:189], v[50:53]
	s_barrier
	s_add_i32 s39, s92, 2
	s_cmpk_gt_u32 s92, 0x55
	s_cbranch_scc1 .LBB0_1005
	s_mov_b32 s92, s39
	s_branch .LBB0_999
